# final-norm pipelined + out-proj/FFN-down residual epilogues: the 8 per-row-group next-tile unpack waits deferred to one wait at the end
# speedup vs baseline: 1.0053x; 1.0001x over previous
.LBB0_1117:
	s_or_b64 exec, exec, s[46:47]
	v_lshl_or_b32 v132, s73, 8, v236
	v_lshl_add_u32 v134, s20, 8, v205
	s_waitcnt lgkmcnt(0)
	v_cndmask_b32_e64 v135, 0, 1, s[38:39]
	v_ashrrev_i32_e32 v133, 31, v132
	v_cmp_ne_u32_e64 s[46:47], 1, v135
	s_andn2_b64 vcc, exec, s[38:39]
	v_ashrrev_i32_e32 v135, 31, v134
	s_cbranch_vccnz .LBB0_1119
	v_lshlrev_b64 v[2:3], 12, v[134:135]
	v_lshl_add_u64 v[2:3], s[4:5], 0, v[2:3]
	v_lshl_add_u64 v[2:3], v[132:133], 1, v[2:3]
	global_load_dwordx4 v[6:9], v[2:3], off
	global_load_dwordx4 v[18:21], v[2:3], off offset:256
.LBB0_1119:
	v_max_f32_e64 v139, |v15|, |v15|
	v_max_f32_e64 v147, |v14|, |v14|
	v_rcp_f32_e32 v137, v178
	v_max_f32_e32 v139, v147, v139
	v_max_f32_e64 v147, |v17|, |v17|
	v_max_f32_e64 v150, |v16|, |v16|
	v_max_f32_e32 v147, v150, v147
	v_max_f32_e64 v150, |v25|, |v25|
	v_max_f32_e64 v151, |v24|, |v24|
	v_max_f32_e32 v150, v151, v150
	v_max3_f32 v150, |v22|, |v23|, v150
	v_max3_f32 v139, v139, v147, v150
	v_mul_f32_e32 v147, v14, v137
	v_mul_f32_e32 v150, v15, v137
	v_mul_f32_e32 v151, v16, v137
	v_mul_f32_e32 v152, v17, v137
	v_med3_f32 v147, v147, s2, v235
	v_med3_f32 v150, v150, s2, v235
	v_med3_f32 v151, v151, s2, v235
	v_med3_f32 v152, v152, s2, v235
	v_add_f32_e32 v147, 0x4b400000, v147
	v_add_f32_e32 v150, 0x4b400000, v150
	v_add_f32_e32 v151, 0x4b400000, v151
	v_add_f32_e32 v152, 0x4b400000, v152
	v_perm_b32 v147, v150, v147, s7
	v_perm_b32 v150, v152, v151, s21
	v_or_b32_e32 v150, v150, v147
	v_mul_f32_e32 v147, v22, v137
	v_mul_f32_e32 v151, v23, v137
	v_mul_f32_e32 v152, v24, v137
	v_mul_f32_e32 v153, v25, v137
	v_lshlrev_b64 v[144:145], 12, v[200:201]
	v_med3_f32 v147, v147, s2, v235
	v_med3_f32 v151, v151, s2, v235
	v_med3_f32 v152, v152, s2, v235
	v_med3_f32 v153, v153, s2, v235
	v_lshl_add_u64 v[140:141], s[4:5], 0, v[144:145]
	v_add_f32_e32 v147, 0x4b400000, v147
	v_add_f32_e32 v151, 0x4b400000, v151
	v_add_f32_e32 v152, 0x4b400000, v152
	v_add_f32_e32 v153, 0x4b400000, v153
	v_lshl_add_u64 v[148:149], v[130:131], 1, v[140:141]
	v_cvt_pk_bf16_f32 v140, v14, v15
	v_cvt_pk_bf16_f32 v141, v16, v17
	v_cvt_pk_bf16_f32 v142, v22, v23
	v_cvt_pk_bf16_f32 v143, v24, v25
	v_perm_b32 v147, v151, v147, s7
	v_perm_b32 v151, v153, v152, s21
	global_store_dwordx4 v[148:149], v[140:143], off
	v_or_b32_e32 v151, v151, v147
	v_lshlrev_b32_e32 v147, 16, v140
	v_and_b32_e32 v140, 0xffff0000, v140
	v_mul_f32_e32 v140, v140, v140
	v_fmac_f32_e32 v140, v147, v147
	v_lshlrev_b32_e32 v147, 16, v141
	v_and_b32_e32 v141, 0xffff0000, v141
	v_mul_f32_e32 v141, v141, v141
	v_fmac_f32_e32 v141, v147, v147
	v_add_f32_e32 v140, v140, v141
	v_lshlrev_b32_e32 v141, 16, v142
	v_and_b32_e32 v142, 0xffff0000, v142
	v_mul_f32_e32 v142, v142, v142
	v_fmac_f32_e32 v142, v141, v141
	v_lshlrev_b32_e32 v141, 16, v143
	v_and_b32_e32 v143, 0xffff0000, v143
	v_mul_f32_e32 v143, v143, v143
	v_fmac_f32_e32 v143, v141, v141
	v_lshl_add_u64 v[144:145], s[16:17], 0, v[144:145]
	v_add_f32_e32 v141, v142, v143
	v_lshl_add_u64 v[144:145], v[144:145], 0, v[130:131]
	v_add_f32_e32 v147, v141, v140
	v_cvt_pk_bf16_f32 v140, v26, v27
	v_cvt_pk_bf16_f32 v141, v28, v29
	v_cvt_pk_bf16_f32 v142, v34, v35
	v_cvt_pk_bf16_f32 v143, v36, v37
	global_store_dwordx2 v[144:145], v[150:151], off offset:2048
	global_store_dwordx4 v[148:149], v[140:143], off offset:256
	v_max_f32_e64 v148, |v27|, |v27|
	v_max_f32_e64 v149, |v26|, |v26|
	v_max_f32_e32 v148, v149, v148
	v_max_f32_e64 v149, |v29|, |v29|
	v_max_f32_e64 v150, |v28|, |v28|
	v_max_f32_e32 v149, v150, v149
	v_max_f32_e64 v150, |v37|, |v37|
	v_max_f32_e64 v151, |v36|, |v36|
	v_max_f32_e32 v150, v151, v150
	v_max3_f32 v150, |v34|, |v35|, v150
	v_max3_f32 v148, v148, v149, v150
	v_max3_f32 v149, v139, 0, v148
	v_mul_f32_e32 v139, v26, v137
	v_mul_f32_e32 v148, v27, v137
	v_mul_f32_e32 v150, v28, v137
	v_mul_f32_e32 v151, v29, v137
	v_med3_f32 v139, v139, s2, v235
	v_med3_f32 v148, v148, s2, v235
	v_med3_f32 v150, v150, s2, v235
	v_med3_f32 v151, v151, s2, v235
	v_add_f32_e32 v139, 0x4b400000, v139
	v_add_f32_e32 v148, 0x4b400000, v148
	v_add_f32_e32 v150, 0x4b400000, v150
	v_add_f32_e32 v151, 0x4b400000, v151
	v_perm_b32 v139, v148, v139, s7
	v_perm_b32 v148, v151, v150, s21
	v_or_b32_e32 v148, v148, v139
	v_mul_f32_e32 v139, v34, v137
	v_med3_f32 v139, v139, s2, v235
	v_add_f32_e32 v150, 0x4b400000, v139
	v_mul_f32_e32 v139, v35, v137
	v_med3_f32 v139, v139, s2, v235
	v_add_f32_e32 v151, 0x4b400000, v139
	v_mul_f32_e32 v139, v36, v137
	v_med3_f32 v139, v139, s2, v235
	v_add_f32_e32 v152, 0x4b400000, v139
	v_lshlrev_b32_e32 v139, 16, v140
	v_and_b32_e32 v140, 0xffff0000, v140
	v_mul_f32_e32 v140, v140, v140
	v_fmac_f32_e32 v140, v139, v139
	v_lshlrev_b32_e32 v139, 16, v141
	v_and_b32_e32 v141, 0xffff0000, v141
	v_mul_f32_e32 v141, v141, v141
	v_fmac_f32_e32 v141, v139, v139
	v_add_f32_e32 v139, v140, v141
	v_and_b32_e32 v141, 0xffff0000, v142
	v_lshlrev_b32_e32 v140, 16, v142
	v_mul_f32_e32 v141, v141, v141
	v_and_b32_e32 v142, 0xffff0000, v143
	v_fmac_f32_e32 v141, v140, v140
	v_lshlrev_b32_e32 v140, 16, v143
	v_mul_f32_e32 v142, v142, v142
	v_fmac_f32_e32 v142, v140, v140
	v_add_f32_e32 v139, v139, v147
	v_add_f32_e32 v140, v141, v142
	v_add_f32_e32 v139, v140, v139
	ds_bpermute_b32 v140, v210, v139
	ds_bpermute_b32 v141, v210, v149
	v_mul_f32_e32 v137, v37, v137
	v_med3_f32 v137, v137, s2, v235
	v_add_f32_e32 v142, 0x4b400000, v137
	s_waitcnt lgkmcnt(1)
	v_add_f32_e32 v137, v139, v140
	s_waitcnt lgkmcnt(0)
	v_max_f32_e32 v140, v141, v141
	v_max_f32_e32 v140, v149, v140
	ds_bpermute_b32 v139, v211, v137
	ds_bpermute_b32 v141, v211, v140
	v_perm_b32 v143, v151, v150, s7
	v_perm_b32 v142, v142, v152, s21
	v_or_b32_e32 v149, v142, v143
	global_store_dwordx2 v[144:145], v[148:149], off offset:2176
	s_and_saveexec_b64 s[38:39], s[44:45]
	s_cbranch_execz .LBB0_1121
	s_waitcnt lgkmcnt(1)
	v_add_f32_e32 v137, v137, v139
	s_waitcnt lgkmcnt(0)
	v_max_f32_e32 v139, v141, v141
	v_max_f32_e32 v140, v140, v140
	v_max_f32_e32 v139, v140, v139
	ds_write_b32 v215, v137
	ds_write_b32 v214, v139
.LBB0_1121:
	s_or_b64 exec, exec, s[38:39]
	s_and_b64 vcc, exec, s[46:47]
	s_cbranch_vccnz .LBB0_1123
	v_or_b32_e32 v14, 16, v134
	v_ashrrev_i32_e32 v15, 31, v14
	v_lshlrev_b64 v[14:15], 12, v[14:15]
	v_lshl_add_u64 v[14:15], s[4:5], 0, v[14:15]
	v_lshl_add_u64 v[14:15], v[132:133], 1, v[14:15]
	global_load_dwordx4 v[22:25], v[14:15], off
	global_load_dwordx4 v[34:37], v[14:15], off offset:256
.LBB0_1123:
	s_waitcnt lgkmcnt(1)
	v_max_f32_e64 v139, |v31|, |v31|
	v_max_f32_e64 v147, |v30|, |v30|
	v_rcp_f32_e32 v137, v170
	v_max_f32_e32 v139, v147, v139
	v_max_f32_e64 v147, |v33|, |v33|
	v_max_f32_e64 v150, |v32|, |v32|
	v_max_f32_e32 v147, v150, v147
	v_max_f32_e64 v150, |v41|, |v41|
	v_max_f32_e64 v151, |v40|, |v40|
	v_max_f32_e32 v150, v151, v150
	v_max3_f32 v150, |v38|, |v39|, v150
	v_max3_f32 v139, v139, v147, v150
	v_mul_f32_e32 v147, v30, v137
	v_mul_f32_e32 v150, v31, v137
	v_mul_f32_e32 v151, v32, v137
	v_mul_f32_e32 v152, v33, v137
	v_med3_f32 v147, v147, s2, v235
	v_med3_f32 v150, v150, s2, v235
	v_med3_f32 v151, v151, s2, v235
	v_med3_f32 v152, v152, s2, v235
	v_add_f32_e32 v147, 0x4b400000, v147
	v_add_f32_e32 v150, 0x4b400000, v150
	v_add_f32_e32 v151, 0x4b400000, v151
	v_add_f32_e32 v152, 0x4b400000, v152
	v_perm_b32 v147, v150, v147, s7
	v_perm_b32 v150, v152, v151, s21
	v_or_b32_e32 v150, v150, v147
	v_mul_f32_e32 v147, v38, v137
	v_mul_f32_e32 v151, v39, v137
	v_mul_f32_e32 v152, v40, v137
	v_mul_f32_e32 v153, v41, v137
	v_lshlrev_b64 v[144:145], 12, v[198:199]
	v_med3_f32 v147, v147, s2, v235
	v_med3_f32 v151, v151, s2, v235
	v_med3_f32 v152, v152, s2, v235
	v_med3_f32 v153, v153, s2, v235
	s_waitcnt lgkmcnt(0)
	v_lshl_add_u64 v[140:141], s[4:5], 0, v[144:145]
	v_add_f32_e32 v147, 0x4b400000, v147
	v_add_f32_e32 v151, 0x4b400000, v151
	v_add_f32_e32 v152, 0x4b400000, v152
	v_add_f32_e32 v153, 0x4b400000, v153
	v_lshl_add_u64 v[148:149], v[130:131], 1, v[140:141]
	v_cvt_pk_bf16_f32 v140, v30, v31
	v_cvt_pk_bf16_f32 v141, v32, v33
	v_cvt_pk_bf16_f32 v142, v38, v39
	v_cvt_pk_bf16_f32 v143, v40, v41
	v_perm_b32 v147, v151, v147, s7
	v_perm_b32 v151, v153, v152, s21
	global_store_dwordx4 v[148:149], v[140:143], off
	v_or_b32_e32 v151, v151, v147
	v_lshlrev_b32_e32 v147, 16, v140
	v_and_b32_e32 v140, 0xffff0000, v140
	v_mul_f32_e32 v140, v140, v140
	v_fmac_f32_e32 v140, v147, v147
	v_lshlrev_b32_e32 v147, 16, v141
	v_and_b32_e32 v141, 0xffff0000, v141
	v_mul_f32_e32 v141, v141, v141
	v_fmac_f32_e32 v141, v147, v147
	v_add_f32_e32 v140, v140, v141
	v_lshlrev_b32_e32 v141, 16, v142
	v_and_b32_e32 v142, 0xffff0000, v142
	v_mul_f32_e32 v142, v142, v142
	v_fmac_f32_e32 v142, v141, v141
	v_lshlrev_b32_e32 v141, 16, v143
	v_and_b32_e32 v143, 0xffff0000, v143
	v_mul_f32_e32 v143, v143, v143
	v_fmac_f32_e32 v143, v141, v141
	v_lshl_add_u64 v[144:145], s[16:17], 0, v[144:145]
	v_add_f32_e32 v141, v142, v143
	v_lshl_add_u64 v[144:145], v[144:145], 0, v[130:131]
	v_add_f32_e32 v147, v141, v140
	v_cvt_pk_bf16_f32 v140, v42, v43
	v_cvt_pk_bf16_f32 v141, v44, v45
	v_cvt_pk_bf16_f32 v142, v50, v51
	v_cvt_pk_bf16_f32 v143, v52, v53
	global_store_dwordx2 v[144:145], v[150:151], off offset:2048
	global_store_dwordx4 v[148:149], v[140:143], off offset:256
	v_max_f32_e64 v148, |v43|, |v43|
	v_max_f32_e64 v149, |v42|, |v42|
	v_max_f32_e32 v148, v149, v148
	v_max_f32_e64 v149, |v45|, |v45|
	v_max_f32_e64 v150, |v44|, |v44|
	v_max_f32_e32 v149, v150, v149
	v_max_f32_e64 v150, |v53|, |v53|
	v_max_f32_e64 v151, |v52|, |v52|
	v_max_f32_e32 v150, v151, v150
	v_max3_f32 v150, |v50|, |v51|, v150
	v_max3_f32 v148, v148, v149, v150
	v_max3_f32 v149, v139, 0, v148
	v_mul_f32_e32 v139, v42, v137
	v_mul_f32_e32 v148, v43, v137
	v_mul_f32_e32 v150, v44, v137
	v_mul_f32_e32 v151, v45, v137
	v_med3_f32 v139, v139, s2, v235
	v_med3_f32 v148, v148, s2, v235
	v_med3_f32 v150, v150, s2, v235
	v_med3_f32 v151, v151, s2, v235
	v_add_f32_e32 v139, 0x4b400000, v139
	v_add_f32_e32 v148, 0x4b400000, v148
	v_add_f32_e32 v150, 0x4b400000, v150
	v_add_f32_e32 v151, 0x4b400000, v151
	v_perm_b32 v139, v148, v139, s7
	v_perm_b32 v148, v151, v150, s21
	v_or_b32_e32 v148, v148, v139
	v_mul_f32_e32 v139, v50, v137
	v_med3_f32 v139, v139, s2, v235
	v_add_f32_e32 v150, 0x4b400000, v139
	v_mul_f32_e32 v139, v51, v137
	v_med3_f32 v139, v139, s2, v235
	v_add_f32_e32 v151, 0x4b400000, v139
	v_mul_f32_e32 v139, v52, v137
	v_med3_f32 v139, v139, s2, v235
	v_add_f32_e32 v152, 0x4b400000, v139
	v_lshlrev_b32_e32 v139, 16, v140
	v_and_b32_e32 v140, 0xffff0000, v140
	v_mul_f32_e32 v140, v140, v140
	v_fmac_f32_e32 v140, v139, v139
	v_lshlrev_b32_e32 v139, 16, v141
	v_and_b32_e32 v141, 0xffff0000, v141
	v_mul_f32_e32 v141, v141, v141
	v_fmac_f32_e32 v141, v139, v139
	v_add_f32_e32 v139, v140, v141
	v_and_b32_e32 v141, 0xffff0000, v142
	v_lshlrev_b32_e32 v140, 16, v142
	v_mul_f32_e32 v141, v141, v141
	v_and_b32_e32 v142, 0xffff0000, v143
	v_fmac_f32_e32 v141, v140, v140
	v_lshlrev_b32_e32 v140, 16, v143
	v_mul_f32_e32 v142, v142, v142
	v_fmac_f32_e32 v142, v140, v140
	v_add_f32_e32 v139, v139, v147
	v_add_f32_e32 v140, v141, v142
	v_add_f32_e32 v139, v140, v139
	ds_bpermute_b32 v140, v210, v139
	ds_bpermute_b32 v141, v210, v149
	v_mul_f32_e32 v137, v53, v137
	v_med3_f32 v137, v137, s2, v235
	v_add_f32_e32 v142, 0x4b400000, v137
	s_waitcnt lgkmcnt(1)
	v_add_f32_e32 v137, v139, v140
	s_waitcnt lgkmcnt(0)
	v_max_f32_e32 v140, v141, v141
	v_max_f32_e32 v140, v149, v140
	ds_bpermute_b32 v139, v211, v137
	ds_bpermute_b32 v141, v211, v140
	v_perm_b32 v143, v151, v150, s7
	v_perm_b32 v142, v142, v152, s21
	v_or_b32_e32 v149, v142, v143
	global_store_dwordx2 v[144:145], v[148:149], off offset:2176
	s_and_saveexec_b64 s[38:39], s[44:45]
	s_cbranch_execz .LBB0_1125
	s_waitcnt lgkmcnt(1)
	v_add_f32_e32 v137, v137, v139
	s_waitcnt lgkmcnt(0)
	v_max_f32_e32 v139, v141, v141
	v_max_f32_e32 v140, v140, v140
	v_max_f32_e32 v139, v140, v139
	ds_write_b32 v217, v137
	ds_write_b32 v216, v139
.LBB0_1125:
	s_or_b64 exec, exec, s[38:39]
	s_and_b64 vcc, exec, s[46:47]
	s_cbranch_vccnz .LBB0_1127
	v_or_b32_e32 v30, 32, v134
	v_ashrrev_i32_e32 v31, 31, v30
	v_lshlrev_b64 v[30:31], 12, v[30:31]
	v_lshl_add_u64 v[30:31], s[4:5], 0, v[30:31]
	v_lshl_add_u64 v[30:31], v[132:133], 1, v[30:31]
	global_load_dwordx4 v[38:41], v[30:31], off
	global_load_dwordx4 v[50:53], v[30:31], off offset:256
.LBB0_1127:
	s_waitcnt lgkmcnt(1)
	v_max_f32_e64 v139, |v47|, |v47|
	v_max_f32_e64 v147, |v46|, |v46|
	v_rcp_f32_e32 v137, v162
	v_max_f32_e32 v139, v147, v139
	v_max_f32_e64 v147, |v49|, |v49|
	v_max_f32_e64 v150, |v48|, |v48|
	v_max_f32_e32 v147, v150, v147
	v_max_f32_e64 v150, |v57|, |v57|
	v_max_f32_e64 v151, |v56|, |v56|
	v_max_f32_e32 v150, v151, v150
	v_max3_f32 v150, |v54|, |v55|, v150
	v_max3_f32 v139, v139, v147, v150
	v_mul_f32_e32 v147, v46, v137
	v_mul_f32_e32 v150, v47, v137
	v_mul_f32_e32 v151, v48, v137
	v_mul_f32_e32 v152, v49, v137
	v_med3_f32 v147, v147, s2, v235
	v_med3_f32 v150, v150, s2, v235
	v_med3_f32 v151, v151, s2, v235
	v_med3_f32 v152, v152, s2, v235
	v_add_f32_e32 v147, 0x4b400000, v147
	v_add_f32_e32 v150, 0x4b400000, v150
	v_add_f32_e32 v151, 0x4b400000, v151
	v_add_f32_e32 v152, 0x4b400000, v152
	v_perm_b32 v147, v150, v147, s7
	v_perm_b32 v150, v152, v151, s21
	v_or_b32_e32 v150, v150, v147
	v_mul_f32_e32 v147, v54, v137
	v_mul_f32_e32 v151, v55, v137
	v_mul_f32_e32 v152, v56, v137
	v_mul_f32_e32 v153, v57, v137
	v_lshlrev_b64 v[144:145], 12, v[196:197]
	v_med3_f32 v147, v147, s2, v235
	v_med3_f32 v151, v151, s2, v235
	v_med3_f32 v152, v152, s2, v235
	v_med3_f32 v153, v153, s2, v235
	s_waitcnt lgkmcnt(0)
	v_lshl_add_u64 v[140:141], s[4:5], 0, v[144:145]
	v_add_f32_e32 v147, 0x4b400000, v147
	v_add_f32_e32 v151, 0x4b400000, v151
	v_add_f32_e32 v152, 0x4b400000, v152
	v_add_f32_e32 v153, 0x4b400000, v153
	v_lshl_add_u64 v[148:149], v[130:131], 1, v[140:141]
	v_cvt_pk_bf16_f32 v140, v46, v47
	v_cvt_pk_bf16_f32 v141, v48, v49
	v_cvt_pk_bf16_f32 v142, v54, v55
	v_cvt_pk_bf16_f32 v143, v56, v57
	v_perm_b32 v147, v151, v147, s7
	v_perm_b32 v151, v153, v152, s21
	global_store_dwordx4 v[148:149], v[140:143], off
	v_or_b32_e32 v151, v151, v147
	v_lshlrev_b32_e32 v147, 16, v140
	v_and_b32_e32 v140, 0xffff0000, v140
	v_mul_f32_e32 v140, v140, v140
	v_fmac_f32_e32 v140, v147, v147
	v_lshlrev_b32_e32 v147, 16, v141
	v_and_b32_e32 v141, 0xffff0000, v141
	v_mul_f32_e32 v141, v141, v141
	v_fmac_f32_e32 v141, v147, v147
	v_add_f32_e32 v140, v140, v141
	v_lshlrev_b32_e32 v141, 16, v142
	v_and_b32_e32 v142, 0xffff0000, v142
	v_mul_f32_e32 v142, v142, v142
	v_fmac_f32_e32 v142, v141, v141
	v_lshlrev_b32_e32 v141, 16, v143
	v_and_b32_e32 v143, 0xffff0000, v143
	v_mul_f32_e32 v143, v143, v143
	v_fmac_f32_e32 v143, v141, v141
	v_lshl_add_u64 v[144:145], s[16:17], 0, v[144:145]
	v_add_f32_e32 v141, v142, v143
	v_lshl_add_u64 v[144:145], v[144:145], 0, v[130:131]
	v_add_f32_e32 v147, v141, v140
	v_cvt_pk_bf16_f32 v140, v58, v59
	v_cvt_pk_bf16_f32 v141, v60, v61
	v_cvt_pk_bf16_f32 v142, v62, v63
	v_cvt_pk_bf16_f32 v143, v64, v65
	global_store_dwordx2 v[144:145], v[150:151], off offset:2048
	global_store_dwordx4 v[148:149], v[140:143], off offset:256
	v_max_f32_e64 v148, |v59|, |v59|
	v_max_f32_e64 v149, |v58|, |v58|
	v_max_f32_e32 v148, v149, v148
	v_max_f32_e64 v149, |v61|, |v61|
	v_max_f32_e64 v150, |v60|, |v60|
	v_max_f32_e32 v149, v150, v149
	v_max_f32_e64 v150, |v65|, |v65|
	v_max_f32_e64 v151, |v64|, |v64|
	v_max_f32_e32 v150, v151, v150
	v_max3_f32 v150, |v62|, |v63|, v150
	v_max3_f32 v148, v148, v149, v150
	v_max3_f32 v149, v139, 0, v148
	v_mul_f32_e32 v139, v58, v137
	v_mul_f32_e32 v148, v59, v137
	v_mul_f32_e32 v150, v60, v137
	v_mul_f32_e32 v151, v61, v137
	v_med3_f32 v139, v139, s2, v235
	v_med3_f32 v148, v148, s2, v235
	v_med3_f32 v150, v150, s2, v235
	v_med3_f32 v151, v151, s2, v235
	v_add_f32_e32 v139, 0x4b400000, v139
	v_add_f32_e32 v148, 0x4b400000, v148
	v_add_f32_e32 v150, 0x4b400000, v150
	v_add_f32_e32 v151, 0x4b400000, v151
	v_perm_b32 v139, v148, v139, s7
	v_perm_b32 v148, v151, v150, s21
	v_or_b32_e32 v148, v148, v139
	v_mul_f32_e32 v139, v62, v137
	v_med3_f32 v139, v139, s2, v235
	v_add_f32_e32 v150, 0x4b400000, v139
	v_mul_f32_e32 v139, v63, v137
	v_med3_f32 v139, v139, s2, v235
	v_add_f32_e32 v151, 0x4b400000, v139
	v_mul_f32_e32 v139, v64, v137
	v_med3_f32 v139, v139, s2, v235
	v_add_f32_e32 v152, 0x4b400000, v139
	v_lshlrev_b32_e32 v139, 16, v140
	v_and_b32_e32 v140, 0xffff0000, v140
	v_mul_f32_e32 v140, v140, v140
	v_fmac_f32_e32 v140, v139, v139
	v_lshlrev_b32_e32 v139, 16, v141
	v_and_b32_e32 v141, 0xffff0000, v141
	v_mul_f32_e32 v141, v141, v141
	v_fmac_f32_e32 v141, v139, v139
	v_add_f32_e32 v139, v140, v141
	v_and_b32_e32 v141, 0xffff0000, v142
	v_lshlrev_b32_e32 v140, 16, v142
	v_mul_f32_e32 v141, v141, v141
	v_and_b32_e32 v142, 0xffff0000, v143
	v_fmac_f32_e32 v141, v140, v140
	v_lshlrev_b32_e32 v140, 16, v143
	v_mul_f32_e32 v142, v142, v142
	v_fmac_f32_e32 v142, v140, v140
	v_add_f32_e32 v139, v139, v147
	v_add_f32_e32 v140, v141, v142
	v_add_f32_e32 v139, v140, v139
	ds_bpermute_b32 v140, v210, v139
	ds_bpermute_b32 v141, v210, v149
	v_mul_f32_e32 v137, v65, v137
	v_med3_f32 v137, v137, s2, v235
	v_add_f32_e32 v142, 0x4b400000, v137
	s_waitcnt lgkmcnt(1)
	v_add_f32_e32 v137, v139, v140
	s_waitcnt lgkmcnt(0)
	v_max_f32_e32 v140, v141, v141
	v_max_f32_e32 v140, v149, v140
	ds_bpermute_b32 v139, v211, v137
	ds_bpermute_b32 v141, v211, v140
	v_perm_b32 v143, v151, v150, s7
	v_perm_b32 v142, v142, v152, s21
	v_or_b32_e32 v149, v142, v143
	global_store_dwordx2 v[144:145], v[148:149], off offset:2176
	s_and_saveexec_b64 s[38:39], s[44:45]
	s_cbranch_execz .LBB0_1129
	s_waitcnt lgkmcnt(1)
	v_add_f32_e32 v137, v137, v139
	s_waitcnt lgkmcnt(0)
	v_max_f32_e32 v139, v141, v141
	v_max_f32_e32 v140, v140, v140
	v_max_f32_e32 v139, v140, v139
	ds_write_b32 v219, v137
	ds_write_b32 v218, v139
.LBB0_1129:
	s_or_b64 exec, exec, s[38:39]
	s_and_b64 vcc, exec, s[46:47]
	s_cbranch_vccnz .LBB0_1131
	v_or_b32_e32 v46, 48, v134
	v_ashrrev_i32_e32 v47, 31, v46
	v_lshlrev_b64 v[46:47], 12, v[46:47]
	v_lshl_add_u64 v[46:47], s[4:5], 0, v[46:47]
	v_lshl_add_u64 v[46:47], v[132:133], 1, v[46:47]
	global_load_dwordx4 v[54:57], v[46:47], off
	global_load_dwordx4 v[62:65], v[46:47], off offset:256
.LBB0_1131:
	s_waitcnt lgkmcnt(1)
	v_max_f32_e64 v139, |v67|, |v67|
	v_max_f32_e64 v147, |v66|, |v66|
	v_rcp_f32_e32 v137, v154
	v_max_f32_e32 v139, v147, v139
	v_max_f32_e64 v147, |v69|, |v69|
	v_max_f32_e64 v150, |v68|, |v68|
	v_max_f32_e32 v147, v150, v147
	v_max_f32_e64 v150, |v73|, |v73|
	v_max_f32_e64 v151, |v72|, |v72|
	v_max_f32_e32 v150, v151, v150
	v_max3_f32 v150, |v70|, |v71|, v150
	v_max3_f32 v139, v139, v147, v150
	v_mul_f32_e32 v147, v66, v137
	v_mul_f32_e32 v150, v67, v137
	v_mul_f32_e32 v151, v68, v137
	v_mul_f32_e32 v152, v69, v137
	v_med3_f32 v147, v147, s2, v235
	v_med3_f32 v150, v150, s2, v235
	v_med3_f32 v151, v151, s2, v235
	v_med3_f32 v152, v152, s2, v235
	v_add_f32_e32 v147, 0x4b400000, v147
	v_add_f32_e32 v150, 0x4b400000, v150
	v_add_f32_e32 v151, 0x4b400000, v151
	v_add_f32_e32 v152, 0x4b400000, v152
	v_perm_b32 v147, v150, v147, s7
	v_perm_b32 v150, v152, v151, s21
	v_or_b32_e32 v150, v150, v147
	v_mul_f32_e32 v147, v70, v137
	v_mul_f32_e32 v151, v71, v137
	v_mul_f32_e32 v152, v72, v137
	v_mul_f32_e32 v153, v73, v137
	v_lshlrev_b64 v[144:145], 12, v[194:195]
	v_med3_f32 v147, v147, s2, v235
	v_med3_f32 v151, v151, s2, v235
	v_med3_f32 v152, v152, s2, v235
	v_med3_f32 v153, v153, s2, v235
	s_waitcnt lgkmcnt(0)
	v_lshl_add_u64 v[140:141], s[4:5], 0, v[144:145]
	v_add_f32_e32 v147, 0x4b400000, v147
	v_add_f32_e32 v151, 0x4b400000, v151
	v_add_f32_e32 v152, 0x4b400000, v152
	v_add_f32_e32 v153, 0x4b400000, v153
	v_lshl_add_u64 v[148:149], v[130:131], 1, v[140:141]
	v_cvt_pk_bf16_f32 v140, v66, v67
	v_cvt_pk_bf16_f32 v141, v68, v69
	v_cvt_pk_bf16_f32 v142, v70, v71
	v_cvt_pk_bf16_f32 v143, v72, v73
	v_perm_b32 v147, v151, v147, s7
	v_perm_b32 v151, v153, v152, s21
	global_store_dwordx4 v[148:149], v[140:143], off
	v_or_b32_e32 v151, v151, v147
	v_lshlrev_b32_e32 v147, 16, v140
	v_and_b32_e32 v140, 0xffff0000, v140
	v_mul_f32_e32 v140, v140, v140
	v_fmac_f32_e32 v140, v147, v147
	v_lshlrev_b32_e32 v147, 16, v141
	v_and_b32_e32 v141, 0xffff0000, v141
	v_mul_f32_e32 v141, v141, v141
	v_fmac_f32_e32 v141, v147, v147
	v_add_f32_e32 v140, v140, v141
	v_lshlrev_b32_e32 v141, 16, v142
	v_and_b32_e32 v142, 0xffff0000, v142
	v_mul_f32_e32 v142, v142, v142
	v_fmac_f32_e32 v142, v141, v141
	v_lshlrev_b32_e32 v141, 16, v143
	v_and_b32_e32 v143, 0xffff0000, v143
	v_mul_f32_e32 v143, v143, v143
	v_fmac_f32_e32 v143, v141, v141
	v_lshl_add_u64 v[144:145], s[16:17], 0, v[144:145]
	v_add_f32_e32 v141, v142, v143
	v_lshl_add_u64 v[144:145], v[144:145], 0, v[130:131]
	v_add_f32_e32 v147, v141, v140
	v_cvt_pk_bf16_f32 v140, v82, v83
	v_cvt_pk_bf16_f32 v141, v84, v85
	v_cvt_pk_bf16_f32 v142, v90, v91
	v_cvt_pk_bf16_f32 v143, v92, v93
	global_store_dwordx2 v[144:145], v[150:151], off offset:2048
	global_store_dwordx4 v[148:149], v[140:143], off offset:256
	v_max_f32_e64 v148, |v83|, |v83|
	v_max_f32_e64 v149, |v82|, |v82|
	v_max_f32_e32 v148, v149, v148
	v_max_f32_e64 v149, |v85|, |v85|
	v_max_f32_e64 v150, |v84|, |v84|
	v_max_f32_e32 v149, v150, v149
	v_max_f32_e64 v150, |v93|, |v93|
	v_max_f32_e64 v151, |v92|, |v92|
	v_max_f32_e32 v150, v151, v150
	v_max3_f32 v150, |v90|, |v91|, v150
	v_max3_f32 v148, v148, v149, v150
	v_max3_f32 v149, v139, 0, v148
	v_mul_f32_e32 v139, v82, v137
	v_mul_f32_e32 v148, v83, v137
	v_mul_f32_e32 v150, v84, v137
	v_mul_f32_e32 v151, v85, v137
	v_med3_f32 v139, v139, s2, v235
	v_med3_f32 v148, v148, s2, v235
	v_med3_f32 v150, v150, s2, v235
	v_med3_f32 v151, v151, s2, v235
	v_add_f32_e32 v139, 0x4b400000, v139
	v_add_f32_e32 v148, 0x4b400000, v148
	v_add_f32_e32 v150, 0x4b400000, v150
	v_add_f32_e32 v151, 0x4b400000, v151
	v_perm_b32 v139, v148, v139, s7
	v_perm_b32 v148, v151, v150, s21
	v_or_b32_e32 v148, v148, v139
	v_mul_f32_e32 v139, v90, v137
	v_med3_f32 v139, v139, s2, v235
	v_add_f32_e32 v150, 0x4b400000, v139
	v_mul_f32_e32 v139, v91, v137
	v_med3_f32 v139, v139, s2, v235
	v_add_f32_e32 v151, 0x4b400000, v139
	v_mul_f32_e32 v139, v92, v137
	v_med3_f32 v139, v139, s2, v235
	v_add_f32_e32 v152, 0x4b400000, v139
	v_lshlrev_b32_e32 v139, 16, v140
	v_and_b32_e32 v140, 0xffff0000, v140
	v_mul_f32_e32 v140, v140, v140
	v_fmac_f32_e32 v140, v139, v139
	v_lshlrev_b32_e32 v139, 16, v141
	v_and_b32_e32 v141, 0xffff0000, v141
	v_mul_f32_e32 v141, v141, v141
	v_fmac_f32_e32 v141, v139, v139
	v_add_f32_e32 v139, v140, v141
	v_and_b32_e32 v141, 0xffff0000, v142
	v_lshlrev_b32_e32 v140, 16, v142
	v_mul_f32_e32 v141, v141, v141
	v_and_b32_e32 v142, 0xffff0000, v143
	v_fmac_f32_e32 v141, v140, v140
	v_lshlrev_b32_e32 v140, 16, v143
	v_mul_f32_e32 v142, v142, v142
	v_fmac_f32_e32 v142, v140, v140
	v_add_f32_e32 v139, v139, v147
	v_add_f32_e32 v140, v141, v142
	v_add_f32_e32 v139, v140, v139
	ds_bpermute_b32 v140, v210, v139
	ds_bpermute_b32 v141, v210, v149
	v_mul_f32_e32 v137, v93, v137
	v_med3_f32 v137, v137, s2, v235
	v_add_f32_e32 v142, 0x4b400000, v137
	s_waitcnt lgkmcnt(1)
	v_add_f32_e32 v137, v139, v140
	s_waitcnt lgkmcnt(0)
	v_max_f32_e32 v140, v141, v141
	v_max_f32_e32 v140, v149, v140
	ds_bpermute_b32 v139, v211, v137
	ds_bpermute_b32 v141, v211, v140
	v_perm_b32 v143, v151, v150, s7
	v_perm_b32 v142, v142, v152, s21
	v_or_b32_e32 v149, v142, v143
	global_store_dwordx2 v[144:145], v[148:149], off offset:2176
	s_and_saveexec_b64 s[38:39], s[44:45]
	s_cbranch_execz .LBB0_1133
	s_waitcnt lgkmcnt(1)
	v_add_f32_e32 v137, v137, v139
	s_waitcnt lgkmcnt(0)
	v_max_f32_e32 v139, v141, v141
	v_max_f32_e32 v140, v140, v140
	v_max_f32_e32 v139, v140, v139
	ds_write_b32 v221, v137
	ds_write_b32 v220, v139
.LBB0_1133:
	s_or_b64 exec, exec, s[38:39]
	s_and_b64 vcc, exec, s[46:47]
	s_cbranch_vccnz .LBB0_1135
	v_lshlrev_b64 v[66:67], 12, v[134:135]
	v_lshl_add_u64 v[66:67], s[4:5], 0, v[66:67]
	v_lshl_add_u64 v[66:67], v[132:133], 1, v[66:67]
	v_add_co_u32_e32 v68, vcc, 0x80000, v66
	s_mov_b64 s[28:29], 0x80000
	s_nop 0
	v_addc_co_u32_e32 v69, vcc, 0, v67, vcc
	v_lshl_add_u64 v[66:67], v[66:67], 0, s[28:29]
	global_load_dwordx4 v[70:73], v[68:69], off
	global_load_dwordx4 v[90:93], v[66:67], off offset:256
.LBB0_1135:
	s_waitcnt lgkmcnt(1)
	v_max_f32_e64 v139, |v75|, |v75|
	v_max_f32_e64 v148, |v74|, |v74|
	v_rcp_f32_e32 v137, v146
	v_max_f32_e32 v139, v148, v139
	v_max_f32_e64 v148, |v77|, |v77|
	v_max_f32_e64 v149, |v76|, |v76|
	v_max_f32_e32 v148, v149, v148
	v_max_f32_e64 v149, |v81|, |v81|
	v_max_f32_e64 v150, |v80|, |v80|
	v_max_f32_e32 v149, v150, v149
	v_max3_f32 v149, |v78|, |v79|, v149
	v_max3_f32 v139, v139, v148, v149
	v_mul_f32_e32 v148, v74, v137
	v_mul_f32_e32 v149, v75, v137
	v_mul_f32_e32 v150, v76, v137
	v_mul_f32_e32 v151, v77, v137
	v_med3_f32 v148, v148, s2, v235
	v_med3_f32 v149, v149, s2, v235
	v_med3_f32 v150, v150, s2, v235
	v_med3_f32 v151, v151, s2, v235
	v_add_f32_e32 v148, 0x4b400000, v148
	v_add_f32_e32 v149, 0x4b400000, v149
	v_add_f32_e32 v150, 0x4b400000, v150
	v_add_f32_e32 v151, 0x4b400000, v151
	v_perm_b32 v148, v149, v148, s7
	v_perm_b32 v149, v151, v150, s21
	v_or_b32_e32 v148, v149, v148
	v_mul_f32_e32 v149, v78, v137
	v_mul_f32_e32 v150, v79, v137
	v_mul_f32_e32 v151, v80, v137
	v_mul_f32_e32 v152, v81, v137
	v_med3_f32 v149, v149, s2, v235
	v_med3_f32 v150, v150, s2, v235
	v_med3_f32 v151, v151, s2, v235
	v_med3_f32 v152, v152, s2, v235
	v_lshlrev_b64 v[144:145], 12, v[192:193]
	v_add_f32_e32 v149, 0x4b400000, v149
	v_add_f32_e32 v150, 0x4b400000, v150
	v_add_f32_e32 v151, 0x4b400000, v151
	v_add_f32_e32 v152, 0x4b400000, v152
	s_waitcnt lgkmcnt(0)
	v_lshl_add_u64 v[140:141], s[4:5], 0, v[144:145]
	v_perm_b32 v149, v150, v149, s7
	v_perm_b32 v150, v152, v151, s21
	v_lshl_add_u64 v[144:145], s[16:17], 0, v[144:145]
	v_lshl_add_u64 v[146:147], v[130:131], 1, v[140:141]
	v_cvt_pk_bf16_f32 v140, v74, v75
	v_cvt_pk_bf16_f32 v141, v76, v77
	v_cvt_pk_bf16_f32 v142, v78, v79
	v_cvt_pk_bf16_f32 v143, v80, v81
	v_or_b32_e32 v149, v150, v149
	v_lshl_add_u64 v[144:145], v[144:145], 0, v[130:131]
	global_store_dwordx4 v[146:147], v[140:143], off
	global_store_dwordx2 v[144:145], v[148:149], off offset:2048
	v_lshlrev_b32_e32 v148, 16, v140
	v_and_b32_e32 v140, 0xffff0000, v140
	v_mul_f32_e32 v140, v140, v140
	v_fmac_f32_e32 v140, v148, v148
	v_lshlrev_b32_e32 v148, 16, v141
	v_and_b32_e32 v141, 0xffff0000, v141
	v_mul_f32_e32 v141, v141, v141
	v_fmac_f32_e32 v141, v148, v148
	v_add_f32_e32 v140, v140, v141
	v_lshlrev_b32_e32 v141, 16, v142
	v_and_b32_e32 v142, 0xffff0000, v142
	v_mul_f32_e32 v142, v142, v142
	v_fmac_f32_e32 v142, v141, v141
	v_lshlrev_b32_e32 v141, 16, v143
	v_and_b32_e32 v143, 0xffff0000, v143
	v_mul_f32_e32 v143, v143, v143
	v_fmac_f32_e32 v143, v141, v141
	v_add_f32_e32 v141, v142, v143
	v_add_f32_e32 v148, v141, v140
	v_cvt_pk_bf16_f32 v140, v98, v99
	v_cvt_pk_bf16_f32 v141, v100, v101
	v_cvt_pk_bf16_f32 v142, v106, v107
	v_cvt_pk_bf16_f32 v143, v108, v109
	global_store_dwordx4 v[146:147], v[140:143], off offset:256
	v_max_f32_e64 v146, |v99|, |v99|
	v_max_f32_e64 v147, |v98|, |v98|
	v_max_f32_e32 v146, v147, v146
	v_max_f32_e64 v147, |v101|, |v101|
	v_max_f32_e64 v149, |v100|, |v100|
	v_max_f32_e32 v147, v149, v147
	v_max_f32_e64 v149, |v109|, |v109|
	v_max_f32_e64 v150, |v108|, |v108|
	v_max_f32_e32 v149, v150, v149
	v_max3_f32 v149, |v106|, |v107|, v149
	v_max3_f32 v146, v146, v147, v149
	v_max3_f32 v147, v139, 0, v146
	v_mul_f32_e32 v139, v98, v137
	v_mul_f32_e32 v146, v99, v137
	v_mul_f32_e32 v149, v100, v137
	v_mul_f32_e32 v150, v101, v137
	v_med3_f32 v139, v139, s2, v235
	v_med3_f32 v146, v146, s2, v235
	v_med3_f32 v149, v149, s2, v235
	v_med3_f32 v150, v150, s2, v235
	v_add_f32_e32 v139, 0x4b400000, v139
	v_add_f32_e32 v146, 0x4b400000, v146
	v_add_f32_e32 v149, 0x4b400000, v149
	v_add_f32_e32 v150, 0x4b400000, v150
	v_perm_b32 v139, v146, v139, s7
	v_perm_b32 v146, v150, v149, s21
	v_or_b32_e32 v146, v146, v139
	v_mul_f32_e32 v139, v106, v137
	v_med3_f32 v139, v139, s2, v235
	v_add_f32_e32 v149, 0x4b400000, v139
	v_mul_f32_e32 v139, v107, v137
	v_med3_f32 v139, v139, s2, v235
	v_add_f32_e32 v150, 0x4b400000, v139
	v_mul_f32_e32 v139, v108, v137
	v_med3_f32 v139, v139, s2, v235
	v_add_f32_e32 v151, 0x4b400000, v139
	v_lshlrev_b32_e32 v139, 16, v140
	v_and_b32_e32 v140, 0xffff0000, v140
	v_mul_f32_e32 v140, v140, v140
	v_fmac_f32_e32 v140, v139, v139
	v_lshlrev_b32_e32 v139, 16, v141
	v_and_b32_e32 v141, 0xffff0000, v141
	v_mul_f32_e32 v141, v141, v141
	v_fmac_f32_e32 v141, v139, v139
	v_add_f32_e32 v139, v140, v141
	v_and_b32_e32 v141, 0xffff0000, v142
	v_lshlrev_b32_e32 v140, 16, v142
	v_mul_f32_e32 v141, v141, v141
	v_and_b32_e32 v142, 0xffff0000, v143
	v_fmac_f32_e32 v141, v140, v140
	v_lshlrev_b32_e32 v140, 16, v143
	v_mul_f32_e32 v142, v142, v142
	v_fmac_f32_e32 v142, v140, v140
	v_add_f32_e32 v139, v139, v148
	v_add_f32_e32 v140, v141, v142
	v_add_f32_e32 v139, v140, v139
	ds_bpermute_b32 v140, v210, v139
	ds_bpermute_b32 v141, v210, v147
	v_mul_f32_e32 v137, v109, v137
	v_med3_f32 v137, v137, s2, v235
	v_add_f32_e32 v142, 0x4b400000, v137
	s_waitcnt lgkmcnt(1)
	v_add_f32_e32 v137, v139, v140
	s_waitcnt lgkmcnt(0)
	v_max_f32_e32 v140, v141, v141
	v_max_f32_e32 v140, v147, v140
	ds_bpermute_b32 v139, v211, v137
	ds_bpermute_b32 v141, v211, v140
	v_perm_b32 v143, v150, v149, s7
	v_perm_b32 v142, v142, v151, s21
	v_or_b32_e32 v147, v142, v143
	global_store_dwordx2 v[144:145], v[146:147], off offset:2176
	s_and_saveexec_b64 s[38:39], s[44:45]
	s_cbranch_execz .LBB0_1137
	s_waitcnt lgkmcnt(1)
	v_add_f32_e32 v137, v137, v139
	s_waitcnt lgkmcnt(0)
	v_max_f32_e32 v139, v141, v141
	v_max_f32_e32 v140, v140, v140
	v_max_f32_e32 v139, v140, v139
	ds_write_b32 v223, v137
	ds_write_b32 v222, v139
.LBB0_1137:
	s_or_b64 exec, exec, s[38:39]
	s_and_b64 vcc, exec, s[46:47]
	s_cbranch_vccnz .LBB0_1139
	v_lshlrev_b64 v[74:75], 12, v[134:135]
	v_lshl_add_u64 v[74:75], s[4:5], 0, v[74:75]
	v_lshl_add_u64 v[74:75], v[132:133], 1, v[74:75]
	v_add_co_u32_e32 v76, vcc, 0x90000, v74
	s_mov_b64 s[28:29], 0x90000
	s_nop 0
	v_addc_co_u32_e32 v77, vcc, 0, v75, vcc
	v_lshl_add_u64 v[74:75], v[74:75], 0, s[28:29]
	global_load_dwordx4 v[78:81], v[76:77], off
	global_load_dwordx4 v[106:109], v[74:75], off offset:256
.LBB0_1139:
	v_max_f32_e64 v146, |v87|, |v87|
	v_max_f32_e64 v147, |v86|, |v86|
	v_rcp_f32_e32 v137, v138
	v_max_f32_e32 v146, v147, v146
	v_max_f32_e64 v147, |v89|, |v89|
	v_max_f32_e64 v148, |v88|, |v88|
	v_max_f32_e32 v147, v148, v147
	v_max_f32_e64 v148, |v97|, |v97|
	v_max_f32_e64 v149, |v96|, |v96|
	v_max_f32_e32 v148, v149, v148
	v_max3_f32 v148, |v94|, |v95|, v148
	v_max3_f32 v148, v146, v147, v148
	v_mul_f32_e32 v146, v86, v137
	v_mul_f32_e32 v147, v87, v137
	v_mul_f32_e32 v149, v88, v137
	v_mul_f32_e32 v150, v89, v137
	v_med3_f32 v146, v146, s2, v235
	v_med3_f32 v147, v147, s2, v235
	v_med3_f32 v149, v149, s2, v235
	v_med3_f32 v150, v150, s2, v235
	v_add_f32_e32 v146, 0x4b400000, v146
	v_add_f32_e32 v147, 0x4b400000, v147
	v_add_f32_e32 v149, 0x4b400000, v149
	v_add_f32_e32 v150, 0x4b400000, v150
	v_perm_b32 v146, v147, v146, s7
	v_perm_b32 v147, v150, v149, s21
	v_or_b32_e32 v146, v147, v146
	v_mul_f32_e32 v147, v94, v137
	v_mul_f32_e32 v149, v95, v137
	v_mul_f32_e32 v150, v96, v137
	v_mul_f32_e32 v151, v97, v137
	v_med3_f32 v147, v147, s2, v235
	v_med3_f32 v149, v149, s2, v235
	v_med3_f32 v150, v150, s2, v235
	v_med3_f32 v151, v151, s2, v235
	v_lshlrev_b64 v[142:143], 12, v[190:191]
	v_add_f32_e32 v147, 0x4b400000, v147
	v_add_f32_e32 v149, 0x4b400000, v149
	v_add_f32_e32 v150, 0x4b400000, v150
	v_add_f32_e32 v151, 0x4b400000, v151
	s_waitcnt lgkmcnt(1)
	v_lshl_add_u64 v[138:139], s[4:5], 0, v[142:143]
	v_perm_b32 v147, v149, v147, s7
	v_perm_b32 v149, v151, v150, s21
	v_lshl_add_u64 v[142:143], s[16:17], 0, v[142:143]
	v_lshl_add_u64 v[144:145], v[130:131], 1, v[138:139]
	v_cvt_pk_bf16_f32 v138, v86, v87
	v_cvt_pk_bf16_f32 v139, v88, v89
	v_cvt_pk_bf16_f32 v140, v94, v95
	s_waitcnt lgkmcnt(0)
	v_cvt_pk_bf16_f32 v141, v96, v97
	v_or_b32_e32 v147, v149, v147
	v_lshl_add_u64 v[142:143], v[142:143], 0, v[130:131]
	global_store_dwordx4 v[144:145], v[138:141], off
	global_store_dwordx2 v[142:143], v[146:147], off offset:2048
	v_lshlrev_b32_e32 v146, 16, v138
	v_and_b32_e32 v138, 0xffff0000, v138
	v_mul_f32_e32 v138, v138, v138
	v_fmac_f32_e32 v138, v146, v146
	v_lshlrev_b32_e32 v146, 16, v139
	v_and_b32_e32 v139, 0xffff0000, v139
	v_mul_f32_e32 v139, v139, v139
	v_fmac_f32_e32 v139, v146, v146
	v_add_f32_e32 v138, v138, v139
	v_lshlrev_b32_e32 v139, 16, v140
	v_and_b32_e32 v140, 0xffff0000, v140
	v_mul_f32_e32 v140, v140, v140
	v_fmac_f32_e32 v140, v139, v139
	v_lshlrev_b32_e32 v139, 16, v141
	v_and_b32_e32 v141, 0xffff0000, v141
	v_mul_f32_e32 v141, v141, v141
	v_fmac_f32_e32 v141, v139, v139
	v_add_f32_e32 v139, v140, v141
	v_add_f32_e32 v146, v139, v138
	v_cvt_pk_bf16_f32 v138, v114, v115
	v_cvt_pk_bf16_f32 v139, v116, v117
	v_cvt_pk_bf16_f32 v140, v118, v119
	v_cvt_pk_bf16_f32 v141, v120, v121
	global_store_dwordx4 v[144:145], v[138:141], off offset:256
	v_lshlrev_b32_e32 v150, 16, v138
	v_max_f32_e64 v144, |v115|, |v115|
	v_and_b32_e32 v138, 0xffff0000, v138
	v_mul_f32_e32 v138, v138, v138
	v_fmac_f32_e32 v138, v150, v150
	v_lshlrev_b32_e32 v150, 16, v139
	v_and_b32_e32 v139, 0xffff0000, v139
	v_mul_f32_e32 v139, v139, v139
	v_fmac_f32_e32 v139, v150, v150
	v_max_f32_e64 v145, |v114|, |v114|
	v_add_f32_e32 v138, v138, v139
	v_lshlrev_b32_e32 v139, 16, v140
	v_and_b32_e32 v140, 0xffff0000, v140
	v_max_f32_e32 v144, v145, v144
	v_max_f32_e64 v145, |v117|, |v117|
	v_max_f32_e64 v147, |v116|, |v116|
	v_mul_f32_e32 v140, v140, v140
	v_max_f32_e32 v145, v147, v145
	v_max_f32_e64 v147, |v121|, |v121|
	v_max_f32_e64 v149, |v120|, |v120|
	v_fmac_f32_e32 v140, v139, v139
	v_lshlrev_b32_e32 v139, 16, v141
	v_and_b32_e32 v141, 0xffff0000, v141
	v_max_f32_e32 v147, v149, v147
	v_mul_f32_e32 v141, v141, v141
	v_max3_f32 v147, |v118|, |v119|, v147
	v_fmac_f32_e32 v141, v139, v139
	v_max3_f32 v144, v144, v145, v147
	v_add_f32_e32 v138, v138, v146
	v_add_f32_e32 v139, v140, v141
	v_max3_f32 v145, v148, 0, v144
	v_mul_f32_e32 v144, v114, v137
	v_mul_f32_e32 v147, v115, v137
	v_mul_f32_e32 v148, v116, v137
	v_mul_f32_e32 v149, v117, v137
	v_add_f32_e32 v138, v139, v138
	v_med3_f32 v144, v144, s2, v235
	v_med3_f32 v147, v147, s2, v235
	v_med3_f32 v148, v148, s2, v235
	v_med3_f32 v149, v149, s2, v235
	ds_bpermute_b32 v139, v210, v138
	ds_bpermute_b32 v140, v210, v145
	v_add_f32_e32 v144, 0x4b400000, v144
	v_add_f32_e32 v147, 0x4b400000, v147
	v_add_f32_e32 v148, 0x4b400000, v148
	v_add_f32_e32 v149, 0x4b400000, v149
	v_perm_b32 v144, v147, v144, s7
	v_perm_b32 v147, v149, v148, s21
	v_or_b32_e32 v144, v147, v144
	v_mul_f32_e32 v147, v118, v137
	v_mul_f32_e32 v148, v119, v137
	v_mul_f32_e32 v149, v120, v137
	v_mul_f32_e32 v137, v121, v137
	v_med3_f32 v137, v137, s2, v235
	v_add_f32_e32 v141, 0x4b400000, v137
	s_waitcnt lgkmcnt(1)
	v_add_f32_e32 v137, v138, v139
	s_waitcnt lgkmcnt(0)
	v_max_f32_e32 v139, v140, v140
	v_max_f32_e32 v139, v145, v139
	ds_bpermute_b32 v138, v211, v137
	ds_bpermute_b32 v140, v211, v139
	v_med3_f32 v147, v147, s2, v235
	v_med3_f32 v148, v148, s2, v235
	v_med3_f32 v149, v149, s2, v235
	v_add_f32_e32 v147, 0x4b400000, v147
	v_add_f32_e32 v148, 0x4b400000, v148
	v_add_f32_e32 v149, 0x4b400000, v149
	v_perm_b32 v145, v148, v147, s7
	v_perm_b32 v141, v141, v149, s21
	v_or_b32_e32 v145, v141, v145
	global_store_dwordx2 v[142:143], v[144:145], off offset:2176
	s_and_saveexec_b64 s[38:39], s[44:45]
	s_cbranch_execz .LBB0_1141
	s_waitcnt lgkmcnt(1)
	v_add_f32_e32 v137, v137, v138
	s_waitcnt lgkmcnt(0)
	v_max_f32_e32 v138, v140, v140
	v_max_f32_e32 v139, v139, v139
	v_max_f32_e32 v138, v139, v138
	ds_write_b32 v225, v137
	ds_write_b32 v224, v138
.LBB0_1141:
	s_or_b64 exec, exec, s[38:39]
	s_and_b64 vcc, exec, s[46:47]
	s_cbranch_vccnz .LBB0_1143
	v_lshlrev_b64 v[86:87], 12, v[134:135]
	v_lshl_add_u64 v[86:87], s[4:5], 0, v[86:87]
	v_lshl_add_u64 v[86:87], v[132:133], 1, v[86:87]
	v_add_co_u32_e32 v88, vcc, 0xa0000, v86
	s_mov_b64 s[28:29], 0xa0000
	s_nop 0
	v_addc_co_u32_e32 v89, vcc, 0, v87, vcc
	v_lshl_add_u64 v[86:87], v[86:87], 0, s[28:29]
	global_load_dwordx4 v[94:97], v[88:89], off
	global_load_dwordx4 v[118:121], v[86:87], off offset:256
.LBB0_1143:
	v_max_f32_e64 v144, |v103|, |v103|
	v_max_f32_e64 v145, |v102|, |v102|
	v_rcp_f32_e32 v146, v136
	v_max_f32_e32 v144, v145, v144
	v_max_f32_e64 v145, |v105|, |v105|
	v_max_f32_e64 v147, |v104|, |v104|
	s_waitcnt lgkmcnt(0)
	v_lshlrev_b64 v[140:141], 12, v[188:189]
	v_max_f32_e32 v145, v147, v145
	v_max_f32_e64 v147, |v113|, |v113|
	v_max_f32_e64 v148, |v112|, |v112|
	v_lshl_add_u64 v[136:137], s[4:5], 0, v[140:141]
	v_max_f32_e32 v147, v148, v147
	v_lshl_add_u64 v[142:143], v[130:131], 1, v[136:137]
	v_cvt_pk_bf16_f32 v136, v102, v103
	v_max3_f32 v147, |v110|, |v111|, v147
	v_lshl_add_u64 v[140:141], s[16:17], 0, v[140:141]
	v_cvt_pk_bf16_f32 v137, v104, v105
	v_cvt_pk_bf16_f32 v138, v110, v111
	v_cvt_pk_bf16_f32 v139, v112, v113
	v_max3_f32 v147, v144, v145, v147
	v_mul_f32_e32 v144, v102, v146
	v_mul_f32_e32 v145, v103, v146
	v_mul_f32_e32 v148, v104, v146
	v_mul_f32_e32 v149, v105, v146
	v_lshl_add_u64 v[140:141], v[140:141], 0, v[130:131]
	v_and_b32_e32 v131, 0xffff0000, v136
	global_store_dwordx4 v[142:143], v[136:139], off
	v_med3_f32 v144, v144, s2, v235
	v_med3_f32 v145, v145, s2, v235
	v_med3_f32 v148, v148, s2, v235
	v_med3_f32 v149, v149, s2, v235
	v_lshlrev_b32_e32 v130, 16, v136
	v_mul_f32_e32 v131, v131, v131
	v_and_b32_e32 v136, 0xffff0000, v137
	v_add_f32_e32 v144, 0x4b400000, v144
	v_add_f32_e32 v145, 0x4b400000, v145
	v_add_f32_e32 v148, 0x4b400000, v148
	v_add_f32_e32 v149, 0x4b400000, v149
	v_fmac_f32_e32 v131, v130, v130
	v_lshlrev_b32_e32 v130, 16, v137
	v_mul_f32_e32 v136, v136, v136
	v_perm_b32 v144, v145, v144, s7
	v_perm_b32 v145, v149, v148, s21
	v_fmac_f32_e32 v136, v130, v130
	v_or_b32_e32 v144, v145, v144
	v_mul_f32_e32 v145, v110, v146
	v_mul_f32_e32 v148, v111, v146
	v_mul_f32_e32 v149, v112, v146
	v_mul_f32_e32 v150, v113, v146
	v_add_f32_e32 v130, v131, v136
	v_and_b32_e32 v136, 0xffff0000, v138
	v_med3_f32 v145, v145, s2, v235
	v_med3_f32 v148, v148, s2, v235
	v_med3_f32 v149, v149, s2, v235
	v_med3_f32 v150, v150, s2, v235
	v_lshlrev_b32_e32 v131, 16, v138
	v_mul_f32_e32 v136, v136, v136
	v_and_b32_e32 v137, 0xffff0000, v139
	v_add_f32_e32 v145, 0x4b400000, v145
	v_add_f32_e32 v148, 0x4b400000, v148
	v_add_f32_e32 v149, 0x4b400000, v149
	v_add_f32_e32 v150, 0x4b400000, v150
	v_fmac_f32_e32 v136, v131, v131
	v_lshlrev_b32_e32 v131, 16, v139
	v_mul_f32_e32 v137, v137, v137
	v_perm_b32 v145, v148, v145, s7
	v_perm_b32 v148, v150, v149, s21
	v_fmac_f32_e32 v137, v131, v131
	v_or_b32_e32 v145, v148, v145
	v_add_f32_e32 v131, v136, v137
	v_cvt_pk_bf16_f32 v136, v122, v123
	v_cvt_pk_bf16_f32 v137, v124, v125
	v_cvt_pk_bf16_f32 v138, v126, v127
	v_cvt_pk_bf16_f32 v139, v128, v129
	global_store_dwordx2 v[140:141], v[144:145], off offset:2048
	v_add_f32_e32 v130, v131, v130
	global_store_dwordx4 v[142:143], v[136:139], off offset:256
	v_max_f32_e64 v131, |v123|, |v123|
	v_max_f32_e64 v142, |v122|, |v122|
	v_max_f32_e32 v131, v142, v131
	v_max_f32_e64 v142, |v125|, |v125|
	v_max_f32_e64 v143, |v124|, |v124|
	v_max_f32_e32 v142, v143, v142
	v_max_f32_e64 v143, |v129|, |v129|
	v_max_f32_e64 v144, |v128|, |v128|
	v_max_f32_e32 v143, v144, v143
	v_max3_f32 v143, |v126|, |v127|, v143
	v_max3_f32 v131, v131, v142, v143
	v_max3_f32 v143, v147, 0, v131
	v_mul_f32_e32 v131, v122, v146
	v_mul_f32_e32 v142, v123, v146
	v_mul_f32_e32 v144, v124, v146
	v_mul_f32_e32 v145, v125, v146
	v_med3_f32 v131, v131, s2, v235
	v_med3_f32 v142, v142, s2, v235
	v_med3_f32 v144, v144, s2, v235
	v_med3_f32 v145, v145, s2, v235
	v_add_f32_e32 v131, 0x4b400000, v131
	v_add_f32_e32 v142, 0x4b400000, v142
	v_add_f32_e32 v144, 0x4b400000, v144
	v_add_f32_e32 v145, 0x4b400000, v145
	v_perm_b32 v131, v142, v131, s7
	v_perm_b32 v142, v145, v144, s21
	v_or_b32_e32 v142, v142, v131
	v_mul_f32_e32 v131, v126, v146
	v_med3_f32 v131, v131, s2, v235
	v_add_f32_e32 v144, 0x4b400000, v131
	v_mul_f32_e32 v131, v127, v146
	v_med3_f32 v131, v131, s2, v235
	v_add_f32_e32 v145, 0x4b400000, v131
	v_mul_f32_e32 v131, v128, v146
	v_med3_f32 v131, v131, s2, v235
	v_add_f32_e32 v147, 0x4b400000, v131
	v_lshlrev_b32_e32 v131, 16, v136
	v_and_b32_e32 v136, 0xffff0000, v136
	v_mul_f32_e32 v136, v136, v136
	v_fmac_f32_e32 v136, v131, v131
	v_lshlrev_b32_e32 v131, 16, v137
	v_and_b32_e32 v137, 0xffff0000, v137
	v_mul_f32_e32 v137, v137, v137
	v_fmac_f32_e32 v137, v131, v131
	v_add_f32_e32 v131, v136, v137
	v_and_b32_e32 v136, 0xffff0000, v138
	v_add_f32_e32 v130, v131, v130
	v_lshlrev_b32_e32 v131, 16, v138
	v_mul_f32_e32 v136, v136, v136
	v_and_b32_e32 v137, 0xffff0000, v139
	v_fmac_f32_e32 v136, v131, v131
	v_lshlrev_b32_e32 v131, 16, v139
	v_mul_f32_e32 v137, v137, v137
	v_fmac_f32_e32 v137, v131, v131
	v_add_f32_e32 v131, v136, v137
	v_add_f32_e32 v130, v131, v130
	ds_bpermute_b32 v137, v210, v143
	ds_bpermute_b32 v131, v210, v130
	v_mul_f32_e32 v136, v129, v146
	v_med3_f32 v136, v136, s2, v235
	v_add_f32_e32 v138, 0x4b400000, v136
	s_waitcnt lgkmcnt(1)
	v_max_f32_e32 v136, v137, v137
	s_waitcnt lgkmcnt(0)
	v_add_f32_e32 v130, v130, v131
	v_max_f32_e32 v136, v143, v136
	ds_bpermute_b32 v131, v211, v130
	ds_bpermute_b32 v137, v211, v136
	v_perm_b32 v139, v145, v144, s7
	v_perm_b32 v138, v138, v147, s21
	v_or_b32_e32 v143, v138, v139
	global_store_dwordx2 v[140:141], v[142:143], off offset:2176
	s_and_saveexec_b64 s[38:39], s[44:45]
	s_cbranch_execz .LBB0_1145
	s_waitcnt lgkmcnt(1)
	v_add_f32_e32 v130, v130, v131
	s_waitcnt lgkmcnt(0)
	v_max_f32_e32 v131, v137, v137
	v_max_f32_e32 v136, v136, v136
	v_max_f32_e32 v131, v136, v131
	ds_write_b32 v227, v130
	ds_write_b32 v226, v131
.LBB0_1145:
	s_or_b64 exec, exec, s[38:39]
	s_and_b64 vcc, exec, s[46:47]
	s_cbranch_vccnz .LBB0_1147
	v_lshlrev_b64 v[102:103], 12, v[134:135]
	v_lshl_add_u64 v[102:103], s[4:5], 0, v[102:103]
	v_lshl_add_u64 v[102:103], v[132:133], 1, v[102:103]
	v_add_co_u32_e32 v104, vcc, 0xb0000, v102
	s_mov_b64 s[28:29], 0xb0000
	s_nop 0
	v_addc_co_u32_e32 v105, vcc, 0, v103, vcc
	v_lshl_add_u64 v[102:103], v[102:103], 0, s[28:29]
	global_load_dwordx4 v[110:113], v[104:105], off
	global_load_dwordx4 v[126:129], v[102:103], off offset:256
.LBB0_1147:
	s_waitcnt lgkmcnt(0)
	s_barrier
	v_mov_b32_e32 v130, v0
	s_movk_i32 s7, 0x100
	s_nop 0
	v_cmp_gt_i32_e32 vcc, s7, v130
	s_and_saveexec_b64 s[38:39], vcc
	s_cbranch_execz .LBB0_1149
	v_lshl_add_u32 v136, v130, 4, 0
	s_waitcnt lgkmcnt(1)
	v_add_u32_e32 v131, 0x26f80, v136
	ds_read_b128 v[132:135], v131
	s_ashr_i32 s7, s6, 31
	s_ashr_i32 s27, s26, 31
	s_lshl_b64 s[6:7], s[6:7], 13
	s_add_u32 s28, s68, s6
	s_waitcnt lgkmcnt(0)
	v_add_f32_e32 v131, v132, v133
	v_add_f32_e32 v132, v134, v135
	v_add_f32_e32 v132, v131, v132
	v_ashrrev_i32_e32 v131, 31, v130
	s_addc_u32 s29, s69, s7
	v_lshlrev_b64 v[134:135], 5, v[130:131]
	v_lshl_add_u64 v[130:131], s[28:29], 0, v[134:135]
	s_lshl_b64 s[26:27], s[26:27], 2
	v_lshl_add_u64 v[130:131], v[130:131], 0, s[26:27]
	global_store_dword v[130:131], v132, off
	v_add_u32_e32 v130, 0x24f80, v136
	ds_read_b128 v[130:133], v130
	s_add_u32 s6, s70, s6
	s_addc_u32 s7, s71, s7
	s_waitcnt lgkmcnt(0)
	v_max_f32_e32 v133, v133, v133
	v_max_f32_e32 v132, v132, v132
	v_max_f32_e32 v132, v132, v133
	v_max3_f32 v132, v130, v131, v132
	v_lshl_add_u64 v[130:131], s[6:7], 0, v[134:135]
	v_lshl_add_u64 v[130:131], v[130:131], 0, s[26:27]
	global_store_dword v[130:131], v132, off
.LBB0_1149:
	s_or_b64 exec, exec, s[38:39]
	s_and_b64 vcc, exec, s[46:47]
	s_mov_b64 s[6:7], -1
	s_cbranch_vccnz .LBB0_1092
	s_waitcnt vmcnt(0)
	v_lshlrev_b32_e32 v2, 16, v6
	v_and_b32_e32 v3, 0xffff0000, v6
	v_lshlrev_b32_e32 v4, 16, v7
	v_and_b32_e32 v5, 0xffff0000, v7
	v_lshlrev_b32_e32 v6, 16, v8
	v_and_b32_e32 v7, 0xffff0000, v8
	v_lshlrev_b32_e32 v8, 16, v9
	v_and_b32_e32 v9, 0xffff0000, v9
	v_lshlrev_b32_e32 v10, 16, v18
	v_and_b32_e32 v11, 0xffff0000, v18
	v_lshlrev_b32_e32 v12, 16, v19
	v_and_b32_e32 v13, 0xffff0000, v19
	v_lshlrev_b32_e32 v18, 16, v20
	v_and_b32_e32 v19, 0xffff0000, v20
	v_lshlrev_b32_e32 v20, 16, v21
	v_and_b32_e32 v21, 0xffff0000, v21
	v_lshlrev_b32_e32 v14, 16, v22
	v_and_b32_e32 v15, 0xffff0000, v22
	v_lshlrev_b32_e32 v16, 16, v23
	v_and_b32_e32 v17, 0xffff0000, v23
	v_lshlrev_b32_e32 v22, 16, v24
	v_and_b32_e32 v23, 0xffff0000, v24
	v_lshlrev_b32_e32 v24, 16, v25
	v_and_b32_e32 v25, 0xffff0000, v25
	v_lshlrev_b32_e32 v26, 16, v34
	v_and_b32_e32 v27, 0xffff0000, v34
	v_lshlrev_b32_e32 v28, 16, v35
	v_and_b32_e32 v29, 0xffff0000, v35
	v_lshlrev_b32_e32 v34, 16, v36
	v_and_b32_e32 v35, 0xffff0000, v36
	v_lshlrev_b32_e32 v36, 16, v37
	v_and_b32_e32 v37, 0xffff0000, v37
	v_lshlrev_b32_e32 v30, 16, v38
	v_and_b32_e32 v31, 0xffff0000, v38
	v_lshlrev_b32_e32 v32, 16, v39
	v_and_b32_e32 v33, 0xffff0000, v39
	v_lshlrev_b32_e32 v38, 16, v40
	v_and_b32_e32 v39, 0xffff0000, v40
	v_lshlrev_b32_e32 v40, 16, v41
	v_and_b32_e32 v41, 0xffff0000, v41
	v_lshlrev_b32_e32 v42, 16, v50
	v_and_b32_e32 v43, 0xffff0000, v50
	v_lshlrev_b32_e32 v44, 16, v51
	v_and_b32_e32 v45, 0xffff0000, v51
	v_lshlrev_b32_e32 v50, 16, v52
	v_and_b32_e32 v51, 0xffff0000, v52
	v_lshlrev_b32_e32 v52, 16, v53
	v_and_b32_e32 v53, 0xffff0000, v53
	v_lshlrev_b32_e32 v46, 16, v54
	v_and_b32_e32 v47, 0xffff0000, v54
	v_lshlrev_b32_e32 v48, 16, v55
	v_and_b32_e32 v49, 0xffff0000, v55
	v_lshlrev_b32_e32 v54, 16, v56
	v_and_b32_e32 v55, 0xffff0000, v56
	v_lshlrev_b32_e32 v56, 16, v57
	v_and_b32_e32 v57, 0xffff0000, v57
	v_lshlrev_b32_e32 v58, 16, v62
	v_and_b32_e32 v59, 0xffff0000, v62
	v_lshlrev_b32_e32 v60, 16, v63
	v_and_b32_e32 v61, 0xffff0000, v63
	v_lshlrev_b32_e32 v62, 16, v64
	v_and_b32_e32 v63, 0xffff0000, v64
	v_lshlrev_b32_e32 v64, 16, v65
	v_and_b32_e32 v65, 0xffff0000, v65
	v_lshlrev_b32_e32 v66, 16, v70
	v_and_b32_e32 v67, 0xffff0000, v70
	v_lshlrev_b32_e32 v68, 16, v71
	v_and_b32_e32 v69, 0xffff0000, v71
	v_lshlrev_b32_e32 v70, 16, v72
	v_and_b32_e32 v71, 0xffff0000, v72
	v_lshlrev_b32_e32 v72, 16, v73
	v_and_b32_e32 v73, 0xffff0000, v73
	v_lshlrev_b32_e32 v82, 16, v90
	v_and_b32_e32 v83, 0xffff0000, v90
	v_lshlrev_b32_e32 v84, 16, v91
	v_and_b32_e32 v85, 0xffff0000, v91
	v_lshlrev_b32_e32 v90, 16, v92
	v_and_b32_e32 v91, 0xffff0000, v92
	v_lshlrev_b32_e32 v92, 16, v93
	v_and_b32_e32 v93, 0xffff0000, v93
	v_lshlrev_b32_e32 v74, 16, v78
	v_and_b32_e32 v75, 0xffff0000, v78
	v_lshlrev_b32_e32 v76, 16, v79
	v_and_b32_e32 v77, 0xffff0000, v79
	v_lshlrev_b32_e32 v78, 16, v80
	v_and_b32_e32 v79, 0xffff0000, v80
	v_lshlrev_b32_e32 v80, 16, v81
	v_and_b32_e32 v81, 0xffff0000, v81
	v_lshlrev_b32_e32 v98, 16, v106
	v_and_b32_e32 v99, 0xffff0000, v106
	v_lshlrev_b32_e32 v100, 16, v107
	v_and_b32_e32 v101, 0xffff0000, v107
	v_lshlrev_b32_e32 v106, 16, v108
	v_and_b32_e32 v107, 0xffff0000, v108
	v_lshlrev_b32_e32 v108, 16, v109
	v_and_b32_e32 v109, 0xffff0000, v109
	v_lshlrev_b32_e32 v86, 16, v94
	v_and_b32_e32 v87, 0xffff0000, v94
	v_lshlrev_b32_e32 v88, 16, v95
	v_and_b32_e32 v89, 0xffff0000, v95
	v_lshlrev_b32_e32 v94, 16, v96
	v_and_b32_e32 v95, 0xffff0000, v96
	v_lshlrev_b32_e32 v96, 16, v97
	v_and_b32_e32 v97, 0xffff0000, v97
	v_lshlrev_b32_e32 v114, 16, v118
	v_and_b32_e32 v115, 0xffff0000, v118
	v_lshlrev_b32_e32 v116, 16, v119
	v_and_b32_e32 v117, 0xffff0000, v119
	v_lshlrev_b32_e32 v118, 16, v120
	v_and_b32_e32 v119, 0xffff0000, v120
	v_lshlrev_b32_e32 v120, 16, v121
	v_and_b32_e32 v121, 0xffff0000, v121
	v_lshlrev_b32_e32 v102, 16, v110
	v_and_b32_e32 v103, 0xffff0000, v110
	v_lshlrev_b32_e32 v104, 16, v111
	v_and_b32_e32 v105, 0xffff0000, v111
	v_lshlrev_b32_e32 v110, 16, v112
	v_and_b32_e32 v111, 0xffff0000, v112
	v_lshlrev_b32_e32 v112, 16, v113
	v_and_b32_e32 v113, 0xffff0000, v113
	v_lshlrev_b32_e32 v122, 16, v126
	v_and_b32_e32 v123, 0xffff0000, v126
	v_lshlrev_b32_e32 v124, 16, v127
	v_and_b32_e32 v125, 0xffff0000, v127
	v_lshlrev_b32_e32 v126, 16, v128
	v_and_b32_e32 v127, 0xffff0000, v128
	v_lshlrev_b32_e32 v128, 16, v129
	v_and_b32_e32 v129, 0xffff0000, v129
	s_andn2_b64 vcc, exec, s[8:9]
	s_cbranch_vccnz .LBB0_1091
	s_barrier
	s_branch .LBB0_1091

.LBB0_1314:
	s_or_b64 exec, exec, s[44:45]
	v_lshl_or_b32 v140, s69, 8, v236
	v_lshl_add_u32 v142, s70, 8, v205
	v_cndmask_b32_e64 v130, 0, 1, s[38:39]
	v_ashrrev_i32_e32 v141, 31, v140
	v_cmp_ne_u32_e64 s[44:45], 1, v130
	s_andn2_b64 vcc, exec, s[38:39]
	v_ashrrev_i32_e32 v143, 31, v142
	s_cbranch_vccnz .LBB0_1316
	v_lshlrev_b64 v[2:3], 12, v[142:143]
	v_lshl_add_u64 v[2:3], s[6:7], 0, v[2:3]
	v_lshl_add_u64 v[2:3], v[140:141], 1, v[2:3]
	global_load_dwordx4 v[6:9], v[2:3], off
	global_load_dwordx4 v[18:21], v[2:3], off offset:256
.LBB0_1316:
	v_lshlrev_b64 v[134:135], 12, v[194:195]
	s_waitcnt lgkmcnt(0)
	v_lshl_add_u64 v[130:131], s[6:7], 0, v[134:135]
	v_lshl_add_u64 v[134:135], s[4:5], 0, v[134:135]
	v_lshl_add_u64 v[146:147], v[138:139], 1, v[130:131]
	v_cvt_pk_bf16_f32 v130, v14, v15
	v_cvt_pk_bf16_f32 v131, v16, v17
	v_cvt_pk_bf16_f32 v132, v22, v23
	v_cvt_pk_bf16_f32 v133, v24, v25
	s_and_b64 vcc, exec, s[46:47]
	v_lshl_add_u64 v[144:145], v[134:135], 0, v[138:139]
	global_store_dwordx4 v[146:147], v[130:133], off
	s_cbranch_vccnz .LBB0_1318
	v_mul_f32_e32 v134, v14, v154
	v_mul_f32_e32 v135, v15, v154
	v_mul_f32_e32 v136, v16, v154
	v_mul_f32_e32 v137, v17, v154
	v_med3_f32 v134, v134, s2, v235
	v_med3_f32 v135, v135, s2, v235
	v_med3_f32 v136, v136, s2, v235
	v_med3_f32 v137, v137, s2, v235
	v_add_f32_e32 v134, 0x4b400000, v134
	v_add_f32_e32 v135, 0x4b400000, v135
	v_add_f32_e32 v136, 0x4b400000, v136
	v_add_f32_e32 v137, 0x4b400000, v137
	s_mov_b32 s9, 0xc0c0400
	s_mov_b32 s27, 0x4000c0c
	v_perm_b32 v134, v135, v134, s9
	v_perm_b32 v135, v137, v136, s27
	v_or_b32_e32 v134, v135, v134
	v_mul_f32_e32 v135, v22, v154
	v_mul_f32_e32 v136, v23, v154
	v_mul_f32_e32 v137, v24, v154
	v_mul_f32_e32 v155, v25, v154
	v_med3_f32 v135, v135, s2, v235
	v_med3_f32 v136, v136, s2, v235
	v_med3_f32 v137, v137, s2, v235
	v_med3_f32 v155, v155, s2, v235
	v_add_f32_e32 v135, 0x4b400000, v135
	v_add_f32_e32 v136, 0x4b400000, v136
	v_add_f32_e32 v137, 0x4b400000, v137
	v_add_f32_e32 v155, 0x4b400000, v155
	v_perm_b32 v135, v136, v135, s9
	v_perm_b32 v136, v155, v137, s27
	v_or_b32_e32 v135, v136, v135
	global_store_dwordx2 v[144:145], v[134:135], off

.LBB0_1322:
	s_or_b64 exec, exec, s[38:39]
	s_and_b64 vcc, exec, s[44:45]
	s_cbranch_vccnz .LBB0_1324
	v_or_b32_e32 v14, 16, v142
	v_ashrrev_i32_e32 v15, 31, v14
	v_lshlrev_b64 v[14:15], 12, v[14:15]
	v_lshl_add_u64 v[14:15], s[6:7], 0, v[14:15]
	v_lshl_add_u64 v[14:15], v[140:141], 1, v[14:15]
	global_load_dwordx4 v[22:25], v[14:15], off
	global_load_dwordx4 v[34:37], v[14:15], off offset:256
.LBB0_1324:
	v_lshlrev_b64 v[134:135], 12, v[192:193]
	s_waitcnt lgkmcnt(0)
	v_lshl_add_u64 v[130:131], s[6:7], 0, v[134:135]
	v_lshl_add_u64 v[134:135], s[4:5], 0, v[134:135]
	v_lshl_add_u64 v[146:147], v[138:139], 1, v[130:131]
	v_cvt_pk_bf16_f32 v130, v30, v31
	v_cvt_pk_bf16_f32 v131, v32, v33
	v_cvt_pk_bf16_f32 v132, v38, v39
	v_cvt_pk_bf16_f32 v133, v40, v41
	s_and_b64 vcc, exec, s[46:47]
	v_lshl_add_u64 v[144:145], v[134:135], 0, v[138:139]
	global_store_dwordx4 v[146:147], v[130:133], off
	s_cbranch_vccnz .LBB0_1326
	v_mul_f32_e32 v134, v30, v153
	v_mul_f32_e32 v135, v31, v153
	v_mul_f32_e32 v136, v32, v153
	v_mul_f32_e32 v137, v33, v153
	v_med3_f32 v134, v134, s2, v235
	v_med3_f32 v135, v135, s2, v235
	v_med3_f32 v136, v136, s2, v235
	v_med3_f32 v137, v137, s2, v235
	v_add_f32_e32 v134, 0x4b400000, v134
	v_add_f32_e32 v135, 0x4b400000, v135
	v_add_f32_e32 v136, 0x4b400000, v136
	v_add_f32_e32 v137, 0x4b400000, v137
	s_mov_b32 s9, 0xc0c0400
	s_mov_b32 s27, 0x4000c0c
	v_perm_b32 v134, v135, v134, s9
	v_perm_b32 v135, v137, v136, s27
	v_or_b32_e32 v134, v135, v134
	v_mul_f32_e32 v135, v38, v153
	v_mul_f32_e32 v136, v39, v153
	v_mul_f32_e32 v137, v40, v153
	v_mul_f32_e32 v154, v41, v153
	v_med3_f32 v135, v135, s2, v235
	v_med3_f32 v136, v136, s2, v235
	v_med3_f32 v137, v137, s2, v235
	v_med3_f32 v154, v154, s2, v235
	v_add_f32_e32 v135, 0x4b400000, v135
	v_add_f32_e32 v136, 0x4b400000, v136
	v_add_f32_e32 v137, 0x4b400000, v137
	v_add_f32_e32 v154, 0x4b400000, v154
	v_perm_b32 v135, v136, v135, s9
	v_perm_b32 v136, v154, v137, s27
	v_or_b32_e32 v135, v136, v135
	global_store_dwordx2 v[144:145], v[134:135], off

.LBB0_1330:
	s_or_b64 exec, exec, s[38:39]
	s_and_b64 vcc, exec, s[44:45]
	s_cbranch_vccnz .LBB0_1332
	v_or_b32_e32 v30, 32, v142
	v_ashrrev_i32_e32 v31, 31, v30
	v_lshlrev_b64 v[30:31], 12, v[30:31]
	v_lshl_add_u64 v[30:31], s[6:7], 0, v[30:31]
	v_lshl_add_u64 v[30:31], v[140:141], 1, v[30:31]
	global_load_dwordx4 v[38:41], v[30:31], off
	global_load_dwordx4 v[50:53], v[30:31], off offset:256
.LBB0_1332:
	v_lshlrev_b64 v[134:135], 12, v[190:191]
	s_waitcnt lgkmcnt(0)
	v_lshl_add_u64 v[130:131], s[6:7], 0, v[134:135]
	v_lshl_add_u64 v[134:135], s[4:5], 0, v[134:135]
	v_lshl_add_u64 v[146:147], v[138:139], 1, v[130:131]
	v_cvt_pk_bf16_f32 v130, v46, v47
	v_cvt_pk_bf16_f32 v131, v48, v49
	v_cvt_pk_bf16_f32 v132, v54, v55
	v_cvt_pk_bf16_f32 v133, v56, v57
	s_and_b64 vcc, exec, s[46:47]
	v_lshl_add_u64 v[144:145], v[134:135], 0, v[138:139]
	global_store_dwordx4 v[146:147], v[130:133], off
	s_cbranch_vccnz .LBB0_1334
	v_mul_f32_e32 v134, v46, v152
	v_mul_f32_e32 v135, v47, v152
	v_mul_f32_e32 v136, v48, v152
	v_mul_f32_e32 v137, v49, v152
	v_med3_f32 v134, v134, s2, v235
	v_med3_f32 v135, v135, s2, v235
	v_med3_f32 v136, v136, s2, v235
	v_med3_f32 v137, v137, s2, v235
	v_add_f32_e32 v134, 0x4b400000, v134
	v_add_f32_e32 v135, 0x4b400000, v135
	v_add_f32_e32 v136, 0x4b400000, v136
	v_add_f32_e32 v137, 0x4b400000, v137
	s_mov_b32 s9, 0xc0c0400
	s_mov_b32 s27, 0x4000c0c
	v_perm_b32 v134, v135, v134, s9
	v_perm_b32 v135, v137, v136, s27
	v_or_b32_e32 v134, v135, v134
	v_mul_f32_e32 v135, v54, v152
	v_mul_f32_e32 v136, v55, v152
	v_mul_f32_e32 v137, v56, v152
	v_mul_f32_e32 v153, v57, v152
	v_med3_f32 v135, v135, s2, v235
	v_med3_f32 v136, v136, s2, v235
	v_med3_f32 v137, v137, s2, v235
	v_med3_f32 v153, v153, s2, v235
	v_add_f32_e32 v135, 0x4b400000, v135
	v_add_f32_e32 v136, 0x4b400000, v136
	v_add_f32_e32 v137, 0x4b400000, v137
	v_add_f32_e32 v153, 0x4b400000, v153
	v_perm_b32 v135, v136, v135, s9
	v_perm_b32 v136, v153, v137, s27
	v_or_b32_e32 v135, v136, v135
	global_store_dwordx2 v[144:145], v[134:135], off

.LBB0_1338:
	s_or_b64 exec, exec, s[38:39]
	s_and_b64 vcc, exec, s[44:45]
	s_cbranch_vccnz .LBB0_1340
	v_or_b32_e32 v46, 48, v142
	v_ashrrev_i32_e32 v47, 31, v46
	v_lshlrev_b64 v[46:47], 12, v[46:47]
	v_lshl_add_u64 v[46:47], s[6:7], 0, v[46:47]
	v_lshl_add_u64 v[46:47], v[140:141], 1, v[46:47]
	global_load_dwordx4 v[54:57], v[46:47], off
	global_load_dwordx4 v[62:65], v[46:47], off offset:256
.LBB0_1340:
	s_waitcnt lgkmcnt(0)
	v_lshlrev_b64 v[130:131], 12, v[188:189]
	s_mov_b64 s[28:29], 0x80000
	v_lshl_add_u64 v[134:135], v[130:131], 0, s[28:29]
	v_lshl_add_u64 v[130:131], s[6:7], 0, v[134:135]
	v_lshl_add_u64 v[134:135], s[4:5], 0, v[134:135]
	v_lshl_add_u64 v[146:147], v[138:139], 1, v[130:131]
	v_cvt_pk_bf16_f32 v130, v66, v67
	v_cvt_pk_bf16_f32 v131, v68, v69
	v_cvt_pk_bf16_f32 v132, v70, v71
	v_cvt_pk_bf16_f32 v133, v72, v73
	s_and_b64 vcc, exec, s[46:47]
	v_lshl_add_u64 v[144:145], v[134:135], 0, v[138:139]
	global_store_dwordx4 v[146:147], v[130:133], off
	s_cbranch_vccnz .LBB0_1342
	v_mul_f32_e32 v134, v66, v151
	v_mul_f32_e32 v135, v67, v151
	v_mul_f32_e32 v136, v68, v151
	v_mul_f32_e32 v137, v69, v151
	v_med3_f32 v134, v134, s2, v235
	v_med3_f32 v135, v135, s2, v235
	v_med3_f32 v136, v136, s2, v235
	v_med3_f32 v137, v137, s2, v235
	v_add_f32_e32 v134, 0x4b400000, v134
	v_add_f32_e32 v135, 0x4b400000, v135
	v_add_f32_e32 v136, 0x4b400000, v136
	v_add_f32_e32 v137, 0x4b400000, v137
	s_mov_b32 s9, 0xc0c0400
	s_mov_b32 s27, 0x4000c0c
	v_perm_b32 v134, v135, v134, s9
	v_perm_b32 v135, v137, v136, s27
	v_or_b32_e32 v134, v135, v134
	v_mul_f32_e32 v135, v70, v151
	v_mul_f32_e32 v136, v71, v151
	v_mul_f32_e32 v137, v72, v151
	v_mul_f32_e32 v152, v73, v151
	v_med3_f32 v135, v135, s2, v235
	v_med3_f32 v136, v136, s2, v235
	v_med3_f32 v137, v137, s2, v235
	v_med3_f32 v152, v152, s2, v235
	v_add_f32_e32 v135, 0x4b400000, v135
	v_add_f32_e32 v136, 0x4b400000, v136
	v_add_f32_e32 v137, 0x4b400000, v137
	v_add_f32_e32 v152, 0x4b400000, v152
	v_perm_b32 v135, v136, v135, s9
	v_perm_b32 v136, v152, v137, s27
	v_or_b32_e32 v135, v136, v135
	global_store_dwordx2 v[144:145], v[134:135], off

.LBB0_1346:
	s_or_b64 exec, exec, s[38:39]
	s_and_b64 vcc, exec, s[44:45]
	s_cbranch_vccnz .LBB0_1348
	v_lshlrev_b64 v[66:67], 12, v[142:143]
	v_lshl_add_u64 v[66:67], s[6:7], 0, v[66:67]
	v_lshl_add_u64 v[66:67], v[140:141], 1, v[66:67]
	v_add_co_u32_e32 v68, vcc, 0x80000, v66
	s_nop 1
	v_addc_co_u32_e32 v69, vcc, 0, v67, vcc
	v_lshl_add_u64 v[66:67], v[66:67], 0, s[28:29]
	global_load_dwordx4 v[70:73], v[68:69], off
	global_load_dwordx4 v[90:93], v[66:67], off offset:256
.LBB0_1348:
	s_waitcnt lgkmcnt(0)
	v_lshlrev_b64 v[130:131], 12, v[188:189]
	s_mov_b64 s[28:29], 0x90000
	v_lshl_add_u64 v[134:135], v[130:131], 0, s[28:29]
	v_lshl_add_u64 v[130:131], s[6:7], 0, v[134:135]
	v_lshl_add_u64 v[134:135], s[4:5], 0, v[134:135]
	v_lshl_add_u64 v[146:147], v[138:139], 1, v[130:131]
	v_cvt_pk_bf16_f32 v130, v74, v75
	v_cvt_pk_bf16_f32 v131, v76, v77
	v_cvt_pk_bf16_f32 v132, v78, v79
	v_cvt_pk_bf16_f32 v133, v80, v81
	s_and_b64 vcc, exec, s[46:47]
	v_lshl_add_u64 v[144:145], v[134:135], 0, v[138:139]
	global_store_dwordx4 v[146:147], v[130:133], off
	s_cbranch_vccnz .LBB0_1350
	v_mul_f32_e32 v134, v74, v150
	v_mul_f32_e32 v135, v75, v150
	v_mul_f32_e32 v136, v76, v150
	v_mul_f32_e32 v137, v77, v150
	v_med3_f32 v134, v134, s2, v235
	v_med3_f32 v135, v135, s2, v235
	v_med3_f32 v136, v136, s2, v235
	v_med3_f32 v137, v137, s2, v235
	v_add_f32_e32 v134, 0x4b400000, v134
	v_add_f32_e32 v135, 0x4b400000, v135
	v_add_f32_e32 v136, 0x4b400000, v136
	v_add_f32_e32 v137, 0x4b400000, v137
	s_mov_b32 s9, 0xc0c0400
	s_mov_b32 s27, 0x4000c0c
	v_perm_b32 v134, v135, v134, s9
	v_perm_b32 v135, v137, v136, s27
	v_or_b32_e32 v134, v135, v134
	v_mul_f32_e32 v135, v78, v150
	v_mul_f32_e32 v136, v79, v150
	v_mul_f32_e32 v137, v80, v150
	v_mul_f32_e32 v151, v81, v150
	v_med3_f32 v135, v135, s2, v235
	v_med3_f32 v136, v136, s2, v235
	v_med3_f32 v137, v137, s2, v235
	v_med3_f32 v151, v151, s2, v235
	v_add_f32_e32 v135, 0x4b400000, v135
	v_add_f32_e32 v136, 0x4b400000, v136
	v_add_f32_e32 v137, 0x4b400000, v137
	v_add_f32_e32 v151, 0x4b400000, v151
	v_perm_b32 v135, v136, v135, s9
	v_perm_b32 v136, v151, v137, s27
	v_or_b32_e32 v135, v136, v135
	global_store_dwordx2 v[144:145], v[134:135], off

.LBB0_1354:
	s_or_b64 exec, exec, s[38:39]
	s_and_b64 vcc, exec, s[44:45]
	s_cbranch_vccnz .LBB0_1356
	v_lshlrev_b64 v[74:75], 12, v[142:143]
	v_lshl_add_u64 v[74:75], s[6:7], 0, v[74:75]
	v_lshl_add_u64 v[74:75], v[140:141], 1, v[74:75]
	v_add_co_u32_e32 v76, vcc, 0x90000, v74
	s_nop 1
	v_addc_co_u32_e32 v77, vcc, 0, v75, vcc
	v_lshl_add_u64 v[74:75], v[74:75], 0, s[28:29]
	global_load_dwordx4 v[78:81], v[76:77], off
	global_load_dwordx4 v[106:109], v[74:75], off offset:256
.LBB0_1356:
	s_waitcnt lgkmcnt(0)
	v_lshlrev_b64 v[130:131], 12, v[188:189]
	s_mov_b64 s[28:29], 0xa0000
	v_lshl_add_u64 v[134:135], v[130:131], 0, s[28:29]
	v_lshl_add_u64 v[130:131], s[6:7], 0, v[134:135]
	v_lshl_add_u64 v[134:135], s[4:5], 0, v[134:135]
	v_lshl_add_u64 v[146:147], v[138:139], 1, v[130:131]
	v_cvt_pk_bf16_f32 v130, v86, v87
	v_cvt_pk_bf16_f32 v131, v88, v89
	v_cvt_pk_bf16_f32 v132, v94, v95
	v_cvt_pk_bf16_f32 v133, v96, v97
	s_and_b64 vcc, exec, s[46:47]
	v_lshl_add_u64 v[144:145], v[134:135], 0, v[138:139]
	global_store_dwordx4 v[146:147], v[130:133], off
	s_cbranch_vccnz .LBB0_1358
	v_mul_f32_e32 v134, v86, v149
	v_mul_f32_e32 v135, v87, v149
	v_mul_f32_e32 v136, v88, v149
	v_mul_f32_e32 v137, v89, v149
	v_med3_f32 v134, v134, s2, v235
	v_med3_f32 v135, v135, s2, v235
	v_med3_f32 v136, v136, s2, v235
	v_med3_f32 v137, v137, s2, v235
	v_add_f32_e32 v134, 0x4b400000, v134
	v_add_f32_e32 v135, 0x4b400000, v135
	v_add_f32_e32 v136, 0x4b400000, v136
	v_add_f32_e32 v137, 0x4b400000, v137
	s_mov_b32 s9, 0xc0c0400
	s_mov_b32 s27, 0x4000c0c
	v_perm_b32 v134, v135, v134, s9
	v_perm_b32 v135, v137, v136, s27
	v_or_b32_e32 v134, v135, v134
	v_mul_f32_e32 v135, v94, v149
	v_mul_f32_e32 v136, v95, v149
	v_mul_f32_e32 v137, v96, v149
	v_mul_f32_e32 v150, v97, v149
	v_med3_f32 v135, v135, s2, v235
	v_med3_f32 v136, v136, s2, v235
	v_med3_f32 v137, v137, s2, v235
	v_med3_f32 v150, v150, s2, v235
	v_add_f32_e32 v135, 0x4b400000, v135
	v_add_f32_e32 v136, 0x4b400000, v136
	v_add_f32_e32 v137, 0x4b400000, v137
	v_add_f32_e32 v150, 0x4b400000, v150
	v_perm_b32 v135, v136, v135, s9
	v_perm_b32 v136, v150, v137, s27
	v_or_b32_e32 v135, v136, v135
	global_store_dwordx2 v[144:145], v[134:135], off

.LBB0_1362:
	s_or_b64 exec, exec, s[38:39]
	s_and_b64 vcc, exec, s[44:45]
	s_cbranch_vccnz .LBB0_1364
	v_lshlrev_b64 v[86:87], 12, v[142:143]
	v_lshl_add_u64 v[86:87], s[6:7], 0, v[86:87]
	v_lshl_add_u64 v[86:87], v[140:141], 1, v[86:87]
	v_add_co_u32_e32 v88, vcc, 0xa0000, v86
	s_nop 1
	v_addc_co_u32_e32 v89, vcc, 0, v87, vcc
	v_lshl_add_u64 v[86:87], v[86:87], 0, s[28:29]
	global_load_dwordx4 v[94:97], v[88:89], off
	global_load_dwordx4 v[118:121], v[86:87], off offset:256
.LBB0_1364:
	s_waitcnt lgkmcnt(0)
	v_lshlrev_b64 v[130:131], 12, v[188:189]
	s_mov_b64 s[28:29], 0xb0000
	v_lshl_add_u64 v[134:135], v[130:131], 0, s[28:29]
	v_lshl_add_u64 v[130:131], s[6:7], 0, v[134:135]
	v_lshl_add_u64 v[134:135], s[4:5], 0, v[134:135]
	v_lshl_add_u64 v[144:145], v[138:139], 1, v[130:131]
	v_cvt_pk_bf16_f32 v130, v102, v103
	v_cvt_pk_bf16_f32 v131, v104, v105
	v_cvt_pk_bf16_f32 v132, v110, v111
	v_cvt_pk_bf16_f32 v133, v112, v113
	s_and_b64 vcc, exec, s[46:47]
	v_lshl_add_u64 v[138:139], v[134:135], 0, v[138:139]
	global_store_dwordx4 v[144:145], v[130:133], off
	s_cbranch_vccnz .LBB0_1366
	v_mul_f32_e32 v134, v102, v148
	v_mul_f32_e32 v135, v103, v148
	v_mul_f32_e32 v136, v104, v148
	v_mul_f32_e32 v137, v105, v148
	v_med3_f32 v134, v134, s2, v235
	v_med3_f32 v135, v135, s2, v235
	v_med3_f32 v136, v136, s2, v235
	v_med3_f32 v137, v137, s2, v235
	v_add_f32_e32 v134, 0x4b400000, v134
	v_add_f32_e32 v135, 0x4b400000, v135
	v_add_f32_e32 v136, 0x4b400000, v136
	v_add_f32_e32 v137, 0x4b400000, v137
	s_mov_b32 s9, 0xc0c0400
	s_mov_b32 s27, 0x4000c0c
	v_perm_b32 v134, v135, v134, s9
	v_perm_b32 v135, v137, v136, s27
	v_or_b32_e32 v134, v135, v134
	v_mul_f32_e32 v135, v110, v148
	v_mul_f32_e32 v136, v111, v148
	v_mul_f32_e32 v137, v112, v148
	v_mul_f32_e32 v146, v113, v148
	v_med3_f32 v135, v135, s2, v235
	v_med3_f32 v136, v136, s2, v235
	v_med3_f32 v137, v137, s2, v235
	v_med3_f32 v146, v146, s2, v235
	v_add_f32_e32 v135, 0x4b400000, v135
	v_add_f32_e32 v136, 0x4b400000, v136
	v_add_f32_e32 v137, 0x4b400000, v137
	v_add_f32_e32 v146, 0x4b400000, v146
	v_perm_b32 v135, v136, v135, s9
	v_perm_b32 v136, v146, v137, s27
	v_or_b32_e32 v135, v136, v135
	global_store_dwordx2 v[138:139], v[134:135], off

.LBB0_1370:
	s_or_b64 exec, exec, s[38:39]
	s_and_b64 vcc, exec, s[44:45]
	s_cbranch_vccnz .LBB0_1372
	v_lshlrev_b64 v[102:103], 12, v[142:143]
	v_lshl_add_u64 v[102:103], s[6:7], 0, v[102:103]
	v_lshl_add_u64 v[102:103], v[140:141], 1, v[102:103]
	v_add_co_u32_e32 v104, vcc, 0xb0000, v102
	s_nop 1
	v_addc_co_u32_e32 v105, vcc, 0, v103, vcc
	v_lshl_add_u64 v[102:103], v[102:103], 0, s[28:29]
	global_load_dwordx4 v[110:113], v[104:105], off
	global_load_dwordx4 v[126:129], v[102:103], off offset:256
.LBB0_1372:
	s_waitcnt lgkmcnt(0)
	s_barrier
	v_mov_b32_e32 v130, v0
	s_movk_i32 s9, 0x100
	s_nop 0
	v_cmp_gt_i32_e32 vcc, s9, v130
	s_and_saveexec_b64 s[38:39], vcc
	s_cbranch_execz .LBB0_1374
	v_lshl_add_u32 v136, v130, 4, 0
	s_waitcnt lgkmcnt(0)
	v_add_u32_e32 v131, 0x26f80, v136
	ds_read_b128 v[132:135], v131
	s_ashr_i32 s9, s8, 31
	s_ashr_i32 s27, s26, 31
	s_lshl_b64 s[8:9], s[8:9], 13
	s_add_u32 s28, s66, s8
	s_waitcnt lgkmcnt(0)
	v_add_f32_e32 v131, v132, v133
	v_add_f32_e32 v132, v134, v135
	v_add_f32_e32 v132, v131, v132
	v_ashrrev_i32_e32 v131, 31, v130
	s_addc_u32 s29, s67, s9
	v_lshlrev_b64 v[134:135], 5, v[130:131]
	v_lshl_add_u64 v[130:131], s[28:29], 0, v[134:135]
	s_lshl_b64 s[26:27], s[26:27], 2
	v_lshl_add_u64 v[130:131], v[130:131], 0, s[26:27]
	global_store_dword v[130:131], v132, off
	v_add_u32_e32 v130, 0x24f80, v136
	ds_read_b128 v[130:133], v130
	s_add_u32 s8, s64, s8
	s_addc_u32 s9, s65, s9
	s_waitcnt lgkmcnt(0)
	v_max_f32_e32 v133, v133, v133
	v_max_f32_e32 v132, v132, v132
	v_max_f32_e32 v132, v132, v133
	v_max3_f32 v132, v130, v131, v132
	v_lshl_add_u64 v[130:131], s[8:9], 0, v[134:135]
	v_lshl_add_u64 v[130:131], v[130:131], 0, s[26:27]
	global_store_dword v[130:131], v132, off
.LBB0_1374:
	s_or_b64 exec, exec, s[38:39]
	s_and_b64 vcc, exec, s[44:45]
	s_mov_b64 s[8:9], -1
	s_cbranch_vccnz .LBB0_1282
	s_waitcnt vmcnt(0)
	v_lshlrev_b32_e32 v2, 16, v6
	v_and_b32_e32 v3, 0xffff0000, v6
	v_lshlrev_b32_e32 v4, 16, v7
	v_and_b32_e32 v5, 0xffff0000, v7
	v_lshlrev_b32_e32 v6, 16, v8
	v_and_b32_e32 v7, 0xffff0000, v8
	v_lshlrev_b32_e32 v8, 16, v9
	v_and_b32_e32 v9, 0xffff0000, v9
	v_lshlrev_b32_e32 v10, 16, v18
	v_and_b32_e32 v11, 0xffff0000, v18
	v_lshlrev_b32_e32 v12, 16, v19
	v_and_b32_e32 v13, 0xffff0000, v19
	v_lshlrev_b32_e32 v18, 16, v20
	v_and_b32_e32 v19, 0xffff0000, v20
	v_lshlrev_b32_e32 v20, 16, v21
	v_and_b32_e32 v21, 0xffff0000, v21
	v_lshlrev_b32_e32 v14, 16, v22
	v_and_b32_e32 v15, 0xffff0000, v22
	v_lshlrev_b32_e32 v16, 16, v23
	v_and_b32_e32 v17, 0xffff0000, v23
	v_lshlrev_b32_e32 v22, 16, v24
	v_and_b32_e32 v23, 0xffff0000, v24
	v_lshlrev_b32_e32 v24, 16, v25
	v_and_b32_e32 v25, 0xffff0000, v25
	v_lshlrev_b32_e32 v26, 16, v34
	v_and_b32_e32 v27, 0xffff0000, v34
	v_lshlrev_b32_e32 v28, 16, v35
	v_and_b32_e32 v29, 0xffff0000, v35
	v_lshlrev_b32_e32 v34, 16, v36
	v_and_b32_e32 v35, 0xffff0000, v36
	v_lshlrev_b32_e32 v36, 16, v37
	v_and_b32_e32 v37, 0xffff0000, v37
	v_lshlrev_b32_e32 v30, 16, v38
	v_and_b32_e32 v31, 0xffff0000, v38
	v_lshlrev_b32_e32 v32, 16, v39
	v_and_b32_e32 v33, 0xffff0000, v39
	v_lshlrev_b32_e32 v38, 16, v40
	v_and_b32_e32 v39, 0xffff0000, v40
	v_lshlrev_b32_e32 v40, 16, v41
	v_and_b32_e32 v41, 0xffff0000, v41
	v_lshlrev_b32_e32 v42, 16, v50
	v_and_b32_e32 v43, 0xffff0000, v50
	v_lshlrev_b32_e32 v44, 16, v51
	v_and_b32_e32 v45, 0xffff0000, v51
	v_lshlrev_b32_e32 v50, 16, v52
	v_and_b32_e32 v51, 0xffff0000, v52
	v_lshlrev_b32_e32 v52, 16, v53
	v_and_b32_e32 v53, 0xffff0000, v53
	v_lshlrev_b32_e32 v46, 16, v54
	v_and_b32_e32 v47, 0xffff0000, v54
	v_lshlrev_b32_e32 v48, 16, v55
	v_and_b32_e32 v49, 0xffff0000, v55
	v_lshlrev_b32_e32 v54, 16, v56
	v_and_b32_e32 v55, 0xffff0000, v56
	v_lshlrev_b32_e32 v56, 16, v57
	v_and_b32_e32 v57, 0xffff0000, v57
	v_lshlrev_b32_e32 v58, 16, v62
	v_and_b32_e32 v59, 0xffff0000, v62
	v_lshlrev_b32_e32 v60, 16, v63
	v_and_b32_e32 v61, 0xffff0000, v63
	v_lshlrev_b32_e32 v62, 16, v64
	v_and_b32_e32 v63, 0xffff0000, v64
	v_lshlrev_b32_e32 v64, 16, v65
	v_and_b32_e32 v65, 0xffff0000, v65
	v_lshlrev_b32_e32 v66, 16, v70
	v_and_b32_e32 v67, 0xffff0000, v70
	v_lshlrev_b32_e32 v68, 16, v71
	v_and_b32_e32 v69, 0xffff0000, v71
	v_lshlrev_b32_e32 v70, 16, v72
	v_and_b32_e32 v71, 0xffff0000, v72
	v_lshlrev_b32_e32 v72, 16, v73
	v_and_b32_e32 v73, 0xffff0000, v73
	v_lshlrev_b32_e32 v82, 16, v90
	v_and_b32_e32 v83, 0xffff0000, v90
	v_lshlrev_b32_e32 v84, 16, v91
	v_and_b32_e32 v85, 0xffff0000, v91
	v_lshlrev_b32_e32 v90, 16, v92
	v_and_b32_e32 v91, 0xffff0000, v92
	v_lshlrev_b32_e32 v92, 16, v93
	v_and_b32_e32 v93, 0xffff0000, v93
	v_lshlrev_b32_e32 v74, 16, v78
	v_and_b32_e32 v75, 0xffff0000, v78
	v_lshlrev_b32_e32 v76, 16, v79
	v_and_b32_e32 v77, 0xffff0000, v79
	v_lshlrev_b32_e32 v78, 16, v80
	v_and_b32_e32 v79, 0xffff0000, v80
	v_lshlrev_b32_e32 v80, 16, v81
	v_and_b32_e32 v81, 0xffff0000, v81
	v_lshlrev_b32_e32 v98, 16, v106
	v_and_b32_e32 v99, 0xffff0000, v106
	v_lshlrev_b32_e32 v100, 16, v107
	v_and_b32_e32 v101, 0xffff0000, v107
	v_lshlrev_b32_e32 v106, 16, v108
	v_and_b32_e32 v107, 0xffff0000, v108
	v_lshlrev_b32_e32 v108, 16, v109
	v_and_b32_e32 v109, 0xffff0000, v109
	v_lshlrev_b32_e32 v86, 16, v94
	v_and_b32_e32 v87, 0xffff0000, v94
	v_lshlrev_b32_e32 v88, 16, v95
	v_and_b32_e32 v89, 0xffff0000, v95
	v_lshlrev_b32_e32 v94, 16, v96
	v_and_b32_e32 v95, 0xffff0000, v96
	v_lshlrev_b32_e32 v96, 16, v97
	v_and_b32_e32 v97, 0xffff0000, v97
	v_lshlrev_b32_e32 v114, 16, v118
	v_and_b32_e32 v115, 0xffff0000, v118
	v_lshlrev_b32_e32 v116, 16, v119
	v_and_b32_e32 v117, 0xffff0000, v119
	v_lshlrev_b32_e32 v118, 16, v120
	v_and_b32_e32 v119, 0xffff0000, v120
	v_lshlrev_b32_e32 v120, 16, v121
	v_and_b32_e32 v121, 0xffff0000, v121
	v_lshlrev_b32_e32 v102, 16, v110
	v_and_b32_e32 v103, 0xffff0000, v110
	v_lshlrev_b32_e32 v104, 16, v111
	v_and_b32_e32 v105, 0xffff0000, v111
	v_lshlrev_b32_e32 v110, 16, v112
	v_and_b32_e32 v111, 0xffff0000, v112
	v_lshlrev_b32_e32 v112, 16, v113
	v_and_b32_e32 v113, 0xffff0000, v113
	v_lshlrev_b32_e32 v122, 16, v126
	v_and_b32_e32 v123, 0xffff0000, v126
	v_lshlrev_b32_e32 v124, 16, v127
	v_and_b32_e32 v125, 0xffff0000, v127
	v_lshlrev_b32_e32 v126, 16, v128
	v_and_b32_e32 v127, 0xffff0000, v128
	v_lshlrev_b32_e32 v128, 16, v129
	v_and_b32_e32 v129, 0xffff0000, v129
	s_andn2_b64 vcc, exec, s[10:11]
	s_cbranch_vccnz .LBB0_1281
	s_barrier
	s_branch .LBB0_1281
